# rg_tile (both modes): depthwise-conv stage rewritten (11 row loads with wave-uniform offsets instead of 32 separately addressed loads, dead address code removed); first grid barrier counter loads batc
# speedup vs baseline: 1.0262x; 1.0033x over previous
; __device__ __forceinline__ unsigned xb_ld(unsigned* p)              { return __hip_atomic_load(p, __ATOMIC_RELAXED, __HIP_MEMORY_SCOPE_AGENT); }
; __device__ __forceinline__ void xcd_barrier_complete(unsigned* bar, unsigned x, unsigned& nloc, unsigned& nx) {
;     const unsigned G = gridDim.x * gridDim.y * gridDim.z;
;     unsigned sum, cnt, mine, sp = 0u;
;     for (;;) {
;         sum = 0u; cnt = 0u; mine = 0u;
; #pragma unroll
;         for (unsigned j = 0; j < 16; ++j) { const unsigned c = xb_ld(&bar[XB_XCNT(j)]); sum += c; cnt += (c > 0u) ? 1u : 0u; mine = (j == x) ? c : mine; }
;         if (sum == G) break;
;         __builtin_amdgcn_s_sleep(1);
;         if ((++sp & 255u) == 0u) { if (xb_ld(&bar[XB_TMO])) break; if (sp > XB_SPIN_CAP) { atomicAdd(&bar[XB_TMO], 1u); break; } }
;     }
.LBB0_31:
	v_readlane_b32 s6, v249, 29
	s_waitcnt lgkmcnt(0)
	v_readlane_b32 s4, v249, 32
	v_readlane_b32 s5, v249, 33
	s_nop 4
	global_load_dword v0, v16, s[4:5] sc1
	v_readlane_b32 s4, v249, 34
	v_readlane_b32 s5, v249, 35
	s_nop 4
	global_load_dword v1, v16, s[4:5] sc1
	v_readlane_b32 s4, v249, 36
	v_readlane_b32 s5, v249, 37
	s_nop 4
	global_load_dword v2, v16, s[4:5] sc1
	v_readlane_b32 s4, v249, 38
	v_readlane_b32 s5, v249, 39
	s_nop 4
	global_load_dword v3, v16, s[4:5] sc1
	v_readlane_b32 s4, v249, 40
	v_readlane_b32 s5, v249, 41
	s_nop 4
	global_load_dword v4, v16, s[4:5] sc1
	v_readlane_b32 s4, v249, 42
	v_readlane_b32 s5, v249, 43
	s_nop 4
	global_load_dword v5, v16, s[4:5] sc1
	v_readlane_b32 s4, v249, 44
	v_readlane_b32 s5, v249, 45
	s_nop 4
	global_load_dword v6, v16, s[4:5] sc1
	v_readlane_b32 s4, v249, 46
	v_readlane_b32 s5, v249, 47
	s_nop 4
	global_load_dword v7, v16, s[4:5] sc1
	v_readlane_b32 s4, v249, 48
	v_readlane_b32 s5, v249, 49
	s_nop 4
	global_load_dword v8, v16, s[4:5] sc1
	v_readlane_b32 s4, v249, 50
	v_readlane_b32 s5, v249, 51
	s_nop 4
	global_load_dword v9, v16, s[4:5] sc1
	v_readlane_b32 s4, v249, 52
	v_readlane_b32 s5, v249, 53
	s_nop 4
	global_load_dword v10, v16, s[4:5] sc1
	v_readlane_b32 s4, v249, 54
	v_readlane_b32 s5, v249, 55
	s_nop 4
	global_load_dword v11, v16, s[4:5] sc1
	v_readlane_b32 s4, v249, 56
	v_readlane_b32 s5, v249, 57
	s_nop 4
	global_load_dword v12, v16, s[4:5] sc1
	v_readlane_b32 s4, v249, 58
	v_readlane_b32 s5, v249, 59
	s_nop 4
	global_load_dword v13, v16, s[4:5] sc1
	v_readlane_b32 s4, v249, 60
	v_readlane_b32 s5, v249, 61
	s_nop 4
	global_load_dword v14, v16, s[4:5] sc1
	v_readlane_b32 s4, v249, 62
	v_readlane_b32 s5, v249, 63
	s_nop 4
	global_load_dword v15, v16, s[4:5] sc1
	s_waitcnt vmcnt(0)
	v_add_u32_e32 v17, v1, v0
	v_add_u32_e32 v17, v17, v2
	v_add_u32_e32 v17, v17, v3
	v_add_u32_e32 v17, v17, v4
	v_add_u32_e32 v17, v17, v5
	v_add_u32_e32 v17, v17, v6
	v_add_u32_e32 v17, v17, v7
	v_add_u32_e32 v17, v17, v8
	v_add_u32_e32 v17, v17, v9
	v_add_u32_e32 v17, v17, v10
	v_add_u32_e32 v17, v17, v11
	v_add_u32_e32 v17, v17, v12
	v_add_u32_e32 v17, v17, v13
	v_add_u32_e32 v17, v17, v14
	s_mov_b64 s[4:5], -1
	s_waitcnt vmcnt(0)
	v_add_u32_e32 v17, v17, v15
	v_cmp_eq_u32_e32 vcc, s6, v17
	s_mov_b64 s[6:7], -1
	s_cbranch_vccnz .LBB0_30
	s_and_b32 s4, s10, 0xff
	s_cmp_eq_u32 s4, 0
	s_mov_b64 s[4:5], -1
	s_mov_b64 s[8:9], -1
	s_sleep 1
	s_cbranch_scc1 .LBB0_35
	s_and_b64 vcc, exec, s[8:9]
	s_cbranch_vccz .LBB0_30

; __device__ __forceinline__ bf16_t f2bf(float f) { return (bf16_t)(pack2(f, 0.f) & 0xffffu); }
; __device__ __forceinline__ float bf2f(bf16_t h) { return __uint_as_float(((unsigned)h) << 16); }
; __device__ void rg_tile(unsigned char* lds, const Params& p, int l, int b, int ck, int hh, bool outmode) {
;     ...
;   {
;     const int i = tid & 63, tq = tid >> 6;
;     const int ch = hh * 64 + i;
;     const float* wc = p.in[20] + (size_t)l * 4 * 256 + ch;
;     const float w0 = wc[0], w1 = wc[256], w2 = wc[512], w3 = wc[768];
; #pragma unroll
;     for (int ii = 0; ii < 8; ++ii) {
;       const int tt = tq * 8 + ii;
;       const int tp = t0 + tt;
;       const int tm1 = tp - 1 >= 0 ? tp - 1 : 0, tp1 = tp + 1 < L ? tp + 1 : L - 1, tp2 = tp + 2 < L ? tp + 2 : L - 1;
;       const float z0 = bf2f(z[(size_t)(rowbase + tm1) * ZS + 2816 + ch]);
;       const float z1 = bf2f(z[(size_t)(rowbase + tp) * ZS + 2816 + ch]);
;       const float z2 = bf2f(z[(size_t)(rowbase + tp1) * ZS + 2816 + ch]);
;       const float z3 = bf2f(z[(size_t)(rowbase + tp2) * ZS + 2816 + ch]);
;       float xr = w1 * z1;
;       xr += (tp - 1 >= 0 ? w0 : 0.f) * z0;
;       xr += (tp + 1 < L ? w2 : 0.f) * z2;
;       xr += (tp + 2 < L ? w3 : 0.f) * z3;
;       XR[tt * 65 + i] = xr;
;       XB[tt * 72 + i] = f2bf(xr);
;     }
.LBB0_326:
	s_andn2_b64 vcc, exec, s[0:1]
	s_cbranch_vccnz .LBB0_330
	s_add_i32 s0, s20, 0xfffffdc0
	s_lshr_b32 s1, s0, 2
	s_mul_i32 s2, s1, 0xe38f
	s_lshr_b32 s2, s2, 21
	s_mul_i32 s2, s2, 36
	s_sub_i32 s1, s1, s2
	s_mul_i32 s0, s0, 0xe38f
	s_and_b32 s2, s1, 0xffff
	s_lshr_b32 s3, s0, 23
	v_mov_b32_e32 v29, v195
	s_lshl_b32 s0, s2, 6
	s_lshl_b32 s4, s3, 8
	s_and_b32 s5, s20, 3
	s_add_i32 s1, s0, 0xffffff00
	v_ashrrev_i32_e32 v28, 6, v29
	s_add_i32 s6, s4, 0x4000
	s_lshl_b32 s7, s3, 11
	v_and_b32_e32 v6, 15, v29
	s_cmp_lt_u32 s2, 4
	s_movk_i32 s4, 0x800
	v_lshlrev_b32_e32 v0, 4, v28
	v_ashrrev_i32_e32 v35, 8, v29
	s_cselect_b32 s4, 0x100, s4
	s_cselect_b32 s9, s0, s1
	s_cselect_b32 s6, s6, s7
	v_readfirstlane_b32 s44, v195
	s_mov_b32 s47, s4
	s_mov_b32 s48, s6
	s_mov_b32 s49, s9
	s_lshl_b32 s50, s5, 7
	s_lshr_b32 s44, s44, 6
	s_lshl_b32 s45, s44, 3
	s_add_i32 s45, s45, s49
	s_add_i32 s46, s47, -1
	s_addk_i32 s50, 0x1600
	v_and_b32_e32 v185, 63, v195
	v_lshl_add_u32 v180, v185, 1, s50
	v_readlane_b32 s52, v254, 3
	v_readlane_b32 s53, v254, 4
	s_lshl_b32 s51, s5, 8
	v_lshl_add_u32 v181, v185, 2, s51
	s_nop 4
	global_load_dword v165, v181, s[52:53]
	global_load_dword v166, v181, s[52:53] offset:1024
	global_load_dword v167, v181, s[52:53] offset:2048
	global_load_dword v168, v181, s[52:53] offset:3072
	s_add_i32 s54, s45, s48
	s_mul_i32 s54, s54, 0x1a00
	v_add_u32_e32 v181, s54, v180
	s_add_i32 s55, s45, -1
	s_max_i32 s55, s55, 0
	s_add_i32 s55, s55, s48
	s_mul_i32 s55, s55, 0x1a00
	v_add_u32_e32 v184, s55, v180
	global_load_ushort v154, v184, s[88:89]
	global_load_ushort v155, v181, s[88:89]
	v_add_u32_e32 v181, 0x1a00, v181
	global_load_ushort v156, v181, s[88:89]
	v_add_u32_e32 v181, 0x1a00, v181
	global_load_ushort v157, v181, s[88:89]
	v_add_u32_e32 v181, 0x1a00, v181
	global_load_ushort v158, v181, s[88:89]
	v_add_u32_e32 v181, 0x1a00, v181
	global_load_ushort v159, v181, s[88:89]
	v_add_u32_e32 v181, 0x1a00, v181
	global_load_ushort v160, v181, s[88:89]
	v_add_u32_e32 v181, 0x1a00, v181
	global_load_ushort v161, v181, s[88:89]
	v_add_u32_e32 v181, 0x1a00, v181
	global_load_ushort v162, v181, s[88:89]
	s_add_i32 s55, s45, 8
	s_min_i32 s55, s55, s46
	s_add_i32 s55, s55, s48
	s_mul_i32 s55, s55, 0x1a00
	v_add_u32_e32 v184, s55, v180
	global_load_ushort v163, v184, s[88:89]
	s_add_i32 s55, s45, 9
	s_min_i32 s55, s55, s46
	s_add_i32 s55, s55, s48
	s_mul_i32 s55, s55, 0x1a00
	v_add_u32_e32 v184, s55, v180
	global_load_ushort v164, v184, s[88:89]
	s_mul_i32 s55, s44, 0x820
	v_lshl_add_u32 v182, v185, 2, s55
	s_mul_i32 s55, s44, 0x480
	v_lshl_add_u32 v183, v185, 1, s55
	s_lshl_b32 s0, s5, 6
	v_and_or_b32 v34, v0, 48, v6
	v_lshlrev_b32_e32 v0, 9, v35
	v_or_b32_e32 v2, s0, v34
	v_ashrrev_i32_e32 v1, 31, v0
	v_lshl_add_u64 v[0:1], v[0:1], 2, s[16:17]
	v_lshlrev_b32_e32 v192, 2, v2
	v_lshl_or_b32 v7, v35, 1, 1
	v_lshl_add_u64 v[2:3], v[0:1], 0, v[192:193]
	v_lshlrev_b32_e32 v0, 8, v7
	v_ashrrev_i32_e32 v1, 31, v0
	v_lshl_add_u64 v[0:1], v[0:1], 2, s[16:17]
	v_lshl_add_u64 v[4:5], v[0:1], 0, v[192:193]
	v_and_b32_e32 v0, 0xffffff00, v29
	v_readlane_b32 s22, v254, 1
	v_lshlrev_b32_e32 v18, 3, v28
	v_ashrrev_i32_e32 v1, 31, v0
	v_readlane_b32 s23, v254, 2
	v_add_u32_e32 v26, s9, v18
	v_and_b32_e32 v31, 63, v29
	v_lshl_add_u64 v[0:1], v[0:1], 2, s[22:23]
	v_lshl_add_u64 v[12:13], v[0:1], 0, v[192:193]
	s_add_i32 s8, s6, -1
	v_or_b32_e32 v30, s0, v31
	v_mov_b64_e32 v[0:1], s[88:89]
	v_lshlrev_b32_e32 v192, 1, v30
	s_add_i32 s7, s4, -1
	s_movk_i32 s21, 0x1000
	s_nop 0
	s_nop 0
	v_readlane_b32 s0, v254, 3
	s_nop 0
	s_nop 0
	v_lshlrev_b32_e32 v19, 2, v30
	v_readlane_b32 s1, v254, 4
	s_nop 4
	global_load_dword v10, v19, s[0:1] offset:1024
	global_load_dword v8, v19, s[0:1] offset:2048
	global_load_dword v9, v19, s[0:1] offset:3072
	global_load_dword v11, v19, s[0:1]
	global_load_dword v33, v[2:3], off
	global_load_dword v32, v[4:5], off
	global_load_dword v16, v[12:13], off
	s_nop 0
	s_nop 0
	s_nop 0
	s_nop 0
	s_movk_i32 s22, 0x104
	s_movk_i32 s9, 0x90
	v_or_b32_e32 v49, 7, v26
	v_add_u32_e32 v50, 8, v26
	v_add_u32_e32 v51, 9, v26
	v_ashrrev_i32_e32 v58, 3, v29
	s_nop 0
	s_nop 0
	s_nop 0
	s_nop 0
	s_nop 0
	s_nop 0
	s_nop 0
	s_nop 0
	s_nop 0
	s_nop 0
	s_nop 0
	v_min_i32_e32 v38, s7, v51
	s_nop 0
	s_nop 0
	s_nop 0
	s_nop 0
	v_min_i32_e32 v24, s7, v50
	v_add_u32_e32 v3, s6, v24
	s_nop 0
	v_mad_i64_i32 v[24:25], s[0:1], v3, s92, v[0:1]
	v_lshl_add_u64 v[24:25], v[24:25], 0, v[192:193]
	v_max_i32_e32 v3, 1, v49
	v_add_co_u32_e64 v24, s[0:1], s21, v24
	v_add_u32_e32 v3, s8, v3
	s_nop 0
	v_addc_co_u32_e64 v25, s[0:1], 0, v25, s[0:1]
	v_mad_u64_u32 v[26:27], s[0:1], v3, s92, v[0:1]
	v_lshl_add_u64 v[26:27], v[26:27], 0, v[192:193]
	v_add_co_u32_e64 v26, s[0:1], s21, v26
	v_add_u32_e32 v3, s6, v49
	s_nop 0
	v_addc_co_u32_e64 v27, s[0:1], 0, v27, s[0:1]
	v_mad_i64_i32 v[36:37], s[0:1], v3, s92, v[0:1]
	v_lshl_add_u64 v[36:37], v[36:37], 0, v[192:193]
	v_add_co_u32_e64 v36, s[0:1], s21, v36
	s_nop 1
	v_addc_co_u32_e64 v37, s[0:1], 0, v37, s[0:1]
	global_load_ushort v56, v[24:25], off offset:1536
	global_load_ushort v57, v[26:27], off offset:1536
	s_nop 0
	global_load_ushort v37, v[36:37], off offset:1536
	v_add_u32_e32 v12, s6, v38
	v_mad_i64_i32 v[0:1], s[0:1], v12, s92, v[0:1]
	v_lshl_add_u64 v[0:1], v[0:1], 0, v[192:193]
	v_add_co_u32_e64 v0, s[0:1], s21, v0
	v_lshlrev_b32_e32 v12, 4, v29
	s_nop 0
	v_addc_co_u32_e64 v1, s[0:1], 0, v1, s[0:1]
	v_readlane_b32 s0, v254, 5
	v_ashrrev_i32_e32 v36, 7, v29
	s_or_b32 s0, s5, s0
	v_and_b32_e32 v26, 0x70, v12
	v_and_b32_e32 v12, -4, v36
	v_add_u32_e32 v12, s0, v12
	v_ashrrev_i32_e32 v13, 31, v12
	v_readlane_b32 s6, v251, 22
; __device__ __forceinline__ bf16_t f2bf(float f) { return (bf16_t)(pack2(f, 0.f) & 0xffffu); }
; __device__ __forceinline__ float bf2f(bf16_t h) { return __uint_as_float(((unsigned)h) << 16); }
; __device__ void rg_tile(unsigned char* lds, const Params& p, int l, int b, int ck, int hh, bool outmode) {
;     ...
;     for (int ii = 0; ii < 8; ++ii) {
;       const int tt = tq * 8 + ii;
;       const int tp = t0 + tt;
;       const int tm1 = tp - 1 >= 0 ? tp - 1 : 0, tp1 = tp + 1 < L ? tp + 1 : L - 1, tp2 = tp + 2 < L ? tp + 2 : L - 1;
;       const float z0 = bf2f(z[(size_t)(rowbase + tm1) * ZS + 2816 + ch]);
;       const float z1 = bf2f(z[(size_t)(rowbase + tp) * ZS + 2816 + ch]);
;       const float z2 = bf2f(z[(size_t)(rowbase + tp1) * ZS + 2816 + ch]);
;       const float z3 = bf2f(z[(size_t)(rowbase + tp2) * ZS + 2816 + ch]);
;       float xr = w1 * z1;
;       xr += (tp - 1 >= 0 ? w0 : 0.f) * z0;
;       xr += (tp + 1 < L ? w2 : 0.f) * z2;
;       xr += (tp + 2 < L ? w3 : 0.f) * z3;
;       XR[tt * 65 + i] = xr;
;       XB[tt * 72 + i] = f2bf(xr);
;     }
;     const bf16_t* rgw = (const bf16_t*)(p.ws + OFF_RGW);
; #pragma unroll
;     for (int q = 0; q < 4; ++q) {
;       const int id = tid + 512 * q;
;       const int row = id >> 3, kc = id & 7;
;       *(uint4*)(WT + row * 72 + kc * 8) = *(const uint4*)(rgw + ((size_t)((l * 4 + (row >> 6)) * 4 + hh)) * 4096 + (row & 63) * 64 + kc * 8);
;     }
;   }
;   __syncthreads();
	v_lshlrev_b64 v[12:13], 13, v[12:13]
	v_readlane_b32 s7, v251, 23
	v_lshlrev_b32_e32 v14, 7, v58
	v_and_b32_e32 v192, 0x1f80, v14
	v_lshl_add_u64 v[12:13], s[6:7], 0, v[12:13]
	v_lshl_add_u64 v[12:13], v[12:13], 0, v[192:193]
	v_mov_b32_e32 v27, v193
	v_lshl_add_u64 v[12:13], v[12:13], 0, v[26:27]
	global_load_ushort v59, v[0:1], off offset:1536
	s_nop 0
	global_load_dwordx4 v[12:15], v[12:13], off
	v_add_u32_e32 v0, 0x200, v29
	v_ashrrev_i32_e32 v60, 3, v0
	v_lshlrev_b32_e32 v18, 7, v60
	v_ashrrev_i32_e32 v0, 7, v0
	v_and_b32_e32 v192, 0x1f80, v18
	v_add_u32_e32 v18, 0x400, v29
	v_and_b32_e32 v0, -4, v0
	v_ashrrev_i32_e32 v61, 3, v18
	v_ashrrev_i32_e32 v18, 7, v18
	v_add_u32_e32 v0, s0, v0
	v_and_b32_e32 v18, -4, v18
	v_ashrrev_i32_e32 v1, 31, v0
	v_add_u32_e32 v18, s0, v18
	v_lshlrev_b64 v[0:1], 13, v[0:1]
	v_ashrrev_i32_e32 v19, 31, v18
	v_lshl_add_u64 v[0:1], s[6:7], 0, v[0:1]
	v_lshlrev_b64 v[18:19], 13, v[18:19]
	v_lshlrev_b32_e32 v20, 7, v61
	v_lshl_add_u64 v[0:1], v[0:1], 0, v[192:193]
	v_lshl_add_u64 v[18:19], s[6:7], 0, v[18:19]
	v_and_b32_e32 v192, 0x1f80, v20
	v_lshl_add_u64 v[18:19], v[18:19], 0, v[192:193]
	v_lshl_add_u64 v[0:1], v[0:1], 0, v[26:27]
	v_lshl_add_u64 v[22:23], v[18:19], 0, v[26:27]
	global_load_dwordx4 v[18:21], v[0:1], off
	s_nop 0
	global_load_dwordx4 v[22:25], v[22:23], off
	v_add_u32_e32 v0, 0x600, v29
	v_ashrrev_i32_e32 v62, 3, v0
	v_ashrrev_i32_e32 v0, 7, v0
	v_and_b32_e32 v0, -4, v0
	v_add_u32_e32 v0, s0, v0
	v_ashrrev_i32_e32 v1, 31, v0
	v_lshlrev_b64 v[0:1], 13, v[0:1]
	v_lshlrev_b32_e32 v38, 7, v62
	v_lshl_add_u64 v[0:1], s[6:7], 0, v[0:1]
	v_and_b32_e32 v192, 0x1f80, v38
	v_lshl_add_u64 v[0:1], v[0:1], 0, v[192:193]
	v_lshl_add_u64 v[0:1], v[0:1], 0, v[26:27]
	global_load_dwordx4 v[38:41], v[0:1], off
	v_cmp_gt_i32_e32 vcc, s4, v50
	s_waitcnt vmcnt(0)
	v_lshlrev_b32_e32 v27, 16, v56
	v_lshlrev_b32_e32 v1, 16, v37
	v_cmp_lt_i32_e64 s[0:1], 0, v49
	v_lshlrev_b32_e32 v0, 16, v57
	v_mul_f32_e32 v1, v10, v1
	v_cndmask_b32_e64 v5, 0, v11, s[0:1]
	v_fmac_f32_e32 v1, v5, v0
	v_cndmask_b32_e32 v0, 0, v8, vcc
	v_cmp_gt_i32_e32 vcc, s4, v51
	v_lshlrev_b32_e32 v3, 16, v59
	v_fmac_f32_e32 v1, v0, v27
	v_cndmask_b32_e32 v0, 0, v9, vcc
	v_fmac_f32_e32 v1, v0, v3
	v_add_u32_e32 v0, 0, v26
	v_mad_u64_u32 v[2:3], s[0:1], v58, s9, v[0:1]
	ds_write_b128 v2, v[12:15] offset:25856
	v_mad_u64_u32 v[2:3], s[0:1], v60, s9, v[0:1]
	ds_write_b128 v2, v[18:21] offset:25856
	v_mad_u64_u32 v[2:3], s[0:1], v61, s9, v[0:1]
	v_mad_u64_u32 v[0:1], s[0:1], v62, s9, v[0:1]
	ds_write_b128 v2, v[22:25] offset:25856
	ds_write_b128 v0, v[38:41] offset:25856
	v_and_b32_e32 v0, 48, v29
	v_add_u32_e32 v0, 0, v0
	v_mad_u32_u24 v17, v6, s9, v0
	s_waitcnt vmcnt(0)
	v_lshlrev_b32_e32 v154, 16, v154
	v_lshlrev_b32_e32 v155, 16, v155
	v_lshlrev_b32_e32 v156, 16, v156
	v_lshlrev_b32_e32 v157, 16, v157
	v_lshlrev_b32_e32 v158, 16, v158
	v_lshlrev_b32_e32 v159, 16, v159
	v_lshlrev_b32_e32 v160, 16, v160
	v_lshlrev_b32_e32 v161, 16, v161
	v_lshlrev_b32_e32 v162, 16, v162
	v_lshlrev_b32_e32 v163, 16, v163
	v_lshlrev_b32_e32 v164, 16, v164
	s_cmp_ge_i32 s45, 1
	s_cselect_b64 s[56:57], -1, 0
	s_add_i32 s55, s45, 8
	s_cmp_lt_i32 s55, s47
	s_cselect_b64 s[58:59], -1, 0
	v_cndmask_b32_e64 v169, 0, v165, s[56:57]
	v_cndmask_b32_e64 v170, 0, v167, s[58:59]
	v_cndmask_b32_e64 v171, 0, v168, s[58:59]
	v_mul_f32_e32 v172, v166, v155
	v_fmac_f32_e32 v172, v169, v154
	v_fmac_f32_e32 v172, v167, v156
	v_fmac_f32_e32 v172, v168, v157
	v_mul_f32_e32 v173, v166, v156
	v_fmac_f32_e32 v173, v165, v155
	v_fmac_f32_e32 v173, v167, v157
	v_fmac_f32_e32 v173, v168, v158
	v_mul_f32_e32 v174, v166, v157
	v_fmac_f32_e32 v174, v165, v156
	v_fmac_f32_e32 v174, v167, v158
	v_fmac_f32_e32 v174, v168, v159
	v_mul_f32_e32 v175, v166, v158
	v_fmac_f32_e32 v175, v165, v157
	v_fmac_f32_e32 v175, v167, v159
	v_fmac_f32_e32 v175, v168, v160
	v_mul_f32_e32 v176, v166, v159
	v_fmac_f32_e32 v176, v165, v158
	v_fmac_f32_e32 v176, v167, v160
	v_fmac_f32_e32 v176, v168, v161
	v_mul_f32_e32 v177, v166, v160
	v_fmac_f32_e32 v177, v165, v159
	v_fmac_f32_e32 v177, v167, v161
	v_fmac_f32_e32 v177, v168, v162
	v_mul_f32_e32 v178, v166, v161
	v_fmac_f32_e32 v178, v165, v160
	v_fmac_f32_e32 v178, v167, v162
	v_fmac_f32_e32 v178, v171, v163
	v_mul_f32_e32 v179, v166, v162
	v_fmac_f32_e32 v179, v165, v161
	v_fmac_f32_e32 v179, v170, v163
	v_fmac_f32_e32 v179, v171, v164
	v_cvt_pk_bf16_f32 v184, v172, v172
	ds_write_b32 v182, v172
	ds_write_b16 v183, v184 offset:16640
	v_cvt_pk_bf16_f32 v184, v173, v173
	ds_write_b32 v182, v173 offset:260
	ds_write_b16 v183, v184 offset:16784
	v_cvt_pk_bf16_f32 v184, v174, v174
	ds_write_b32 v182, v174 offset:520
	ds_write_b16 v183, v184 offset:16928
	v_cvt_pk_bf16_f32 v184, v175, v175
	ds_write_b32 v182, v175 offset:780
	ds_write_b16 v183, v184 offset:17072
	v_cvt_pk_bf16_f32 v184, v176, v176
	ds_write_b32 v182, v176 offset:1040
	ds_write_b16 v183, v184 offset:17216
	v_cvt_pk_bf16_f32 v184, v177, v177
	ds_write_b32 v182, v177 offset:1300
	ds_write_b16 v183, v184 offset:17360
	v_cvt_pk_bf16_f32 v184, v178, v178
	ds_write_b32 v182, v178 offset:1560
	ds_write_b16 v183, v184 offset:17504
	v_cvt_pk_bf16_f32 v184, v179, v179
	ds_write_b32 v182, v179 offset:1820
	ds_write_b16 v183, v184 offset:17648
	s_waitcnt lgkmcnt(0)
	s_barrier
; __device__ __forceinline__ float fexp(float x) { return __expf(x); }
; __device__ __forceinline__ float sigm(float x) { return frcp(1.f + fexp(-x)); }
; __device__ __forceinline__ float softplusf(float x) { return fmaxf(x, 0.f) + __logf(1.f + fexp(-fabsf(x))); }
; __device__ void rg_tile(unsigned char* lds, const Params& p, int l, int b, int ck, int hh, bool outmode) {
;     ...
;   {
;     const int d = w >> 2, jf = w & 3;
;     f32x4 ar[4], ai[4];
; #pragma unroll
;     for (int i = 0; i < 4; ++i) { ar[i] = (f32x4){0.f, 0.f, 0.f, 0.f}; ai[i] = (f32x4){0.f, 0.f, 0.f, 0.f}; }
; #pragma unroll
;     for (int ks = 0; ks < 2; ++ks) {
;       const bf16x8 wr = ldfrag(WT + ((d * 2 + 0) * 64 + jf * 16 + lr) * 72 + ks * 32 + lg * 8);
;       const bf16x8 wi = ldfrag(WT + ((d * 2 + 1) * 64 + jf * 16 + lr) * 72 + ks * 32 + lg * 8);
; #pragma unroll
;       for (int tf = 0; tf < 4; ++tf) {
;         const bf16x8 xf = ldfrag(XB + (tf * 16 + lr) * 72 + ks * 32 + lg * 8);
;         ar[tf] = mfma16(xf, wr, ar[tf]);
;         ai[tf] = mfma16(xf, wi, ai[tf]);
;       }
;     }
;     const int j = jf * 16 + lr;
;     const int ch = hh * 64 + j;
;     const float sp = softplusf(-lam_);
; #pragma unroll
;     for (int tf = 0; tf < 4; ++tf)
; #pragma unroll
;       for (int jj = 0; jj < 4; ++jj) {
;         const int tt = tf * 16 + lg * 4 + jj;
;         const float r = sigm(ar[tf][jj] + br);
;         const float ig = sigm(ai[tf][jj] + bi);
;         const float la = -8.0f * r * sp;
;         const float a = fexp(la);
;         const float bq = __builtin_amdgcn_sqrtf(fmaxf(1.f - a * a, 0.f)) * ig * XR[tt * 65 + j];
;         AA[(d * 64 + tt) * 64 + j] = a;
;         BQ[(d * 64 + tt) * 64 + j] = bq;
;       }
	ds_read_b128 v[18:21], v17 offset:16640
	v_lshl_or_b32 v1, v35, 7, v34
	v_mad_u64_u32 v[2:3], s[0:1], v1, s9, v[0:1]
	v_lshl_or_b32 v1, v7, 6, v34
	ds_read_b128 v[12:15], v2 offset:25856
	v_mad_u64_u32 v[0:1], s[0:1], v1, s9, v[0:1]
	ds_read_b128 v[4:7], v2 offset:25920
	ds_read_b128 v[22:25], v17 offset:16704
	ds_read_b128 v[8:11], v0 offset:25856
	ds_read_b128 v[0:3], v0 offset:25920
	s_mov_b32 s0, 0xbfb8aa3b
	v_mul_f32_e64 v26, |v16|, s0
	s_waitcnt lgkmcnt(4)
	v_mfma_f32_16x16x32_bf16 v[38:41], v[18:21], v[12:15], 0
	v_exp_f32_e32 v26, v26
	s_mov_b32 s0, 0x800000
	v_max_f32_e64 v16, -v16, -v16
	s_waitcnt lgkmcnt(1)
	v_mfma_f32_16x16x32_bf16 v[18:21], v[18:21], v[8:11], 0
	v_max_f32_e32 v16, 0, v16
	v_bfe_u32 v62, v29, 4, 2
	ds_read_b128 v[42:45], v17 offset:18944
	ds_read_b128 v[46:49], v17 offset:19008
	s_waitcnt lgkmcnt(2)
	v_mfma_f32_16x16x32_bf16 v[54:57], v[22:25], v[0:3], v[18:21]
	v_lshlrev_b32_e32 v35, 12, v35
	s_nop 1
	v_add_f32_e32 v18, 1.0, v26
	v_cmp_gt_f32_e32 vcc, s0, v18
	v_mfma_f32_16x16x32_bf16 v[38:41], v[22:25], v[4:7], v[38:41]
	s_mov_b32 s0, 0x3f317217
	v_cndmask_b32_e64 v19, 0, 32, vcc
	v_ldexp_f32 v18, v18, v19
	v_log_f32_e32 v18, v18
	v_mov_b32_e32 v20, 0x41b17218
	v_cndmask_b32_e32 v20, 0, v20, vcc
	s_nop 1
	v_add_f32_e32 v39, v33, v39
	v_mul_f32_e32 v19, 0x3f317217, v18
	v_fma_f32 v19, v18, s0, -v19
	v_fmac_f32_e32 v19, 0x3377d1cf, v18
	s_mov_b32 s0, 0x7f800000
	v_fmac_f32_e32 v19, 0x3f317217, v18
	v_cmp_lt_f32_e64 s[0:1], |v18|, s0
	ds_read_b128 v[58:61], v17 offset:21248
	ds_read_b128 v[24:27], v17 offset:21312
	v_cndmask_b32_e64 v18, v18, v19, s[0:1]
	v_add_f32_e32 v19, v33, v38
	v_mul_f32_e32 v19, 0xbfb8aa3b, v19
	v_exp_f32_e32 v19, v19
	v_sub_f32_e32 v18, v18, v20
	v_add_f32_e32 v37, v16, v18
	v_add_f32_e32 v18, v32, v54
	v_add_f32_e32 v16, 1.0, v19
	v_rcp_f32_e32 v16, v16
	v_mul_f32_e32 v18, 0xbfb8aa3b, v18
	v_exp_f32_e32 v18, v18
	v_lshl_add_u32 v54, v34, 2, 0
	v_mul_f32_e32 v16, 0xc1000000, v16
	v_mul_f32_e32 v16, v37, v16
	v_mul_f32_e32 v16, 0x3fb8aa3b, v16
	v_exp_f32_e32 v38, v16
	v_add_f32_e32 v16, 1.0, v18
	v_rcp_f32_e32 v63, v16
	s_movk_i32 s0, 0x410
	v_fma_f32 v16, -v38, v38, 1.0
	v_max_f32_e32 v16, 0, v16
	v_sqrt_f32_e32 v64, v16
	v_mad_u32_u24 v16, v62, s0, v54
	ds_read_b32 v65, v16
	ds_read_b128 v[20:23], v17 offset:23552
	ds_read_b128 v[16:19], v17 offset:23616
	v_mul_f32_e32 v39, 0xbfb8aa3b, v39
	v_mul_f32_e32 v63, v63, v64
	v_lshlrev_b32_e32 v64, 8, v62
	v_or3_b32 v64, v64, v35, v34
	v_exp_f32_e32 v39, v39
	v_lshlrev_b32_e32 v64, 2, v64
	s_waitcnt lgkmcnt(2)
	v_mul_f32_e32 v63, v65, v63
	v_add_u32_e32 v65, 0, v64
	v_readlane_b32 s0, v253, 37
	ds_write_b32 v65, v38 offset:62720
	v_mfma_f32_16x16x32_bf16 v[50:53], v[42:45], v[12:15], 0
	v_add_u32_e32 v38, s0, v64
	ds_write_b32 v38, v63
	v_add_f32_e32 v38, 1.0, v39
	v_add_f32_e32 v39, v32, v55
	v_lshl_or_b32 v55, v62, 2, 1
	v_rcp_f32_e32 v38, v38
	v_mad_u32_u24 v54, v55, s22, v54
	v_lshlrev_b32_e32 v55, 6, v55
	v_or3_b32 v34, v55, v35, v34
	v_add_f32_e32 v35, v33, v40
	v_mul_f32_e32 v35, 0xbfb8aa3b, v35
	v_exp_f32_e32 v35, v35
	v_mul_f32_e32 v38, 0xc1000000, v38
	v_mul_f32_e32 v38, v37, v38
	v_mul_f32_e32 v38, 0x3fb8aa3b, v38
	v_mul_f32_e32 v39, 0xbfb8aa3b, v39
	v_exp_f32_e32 v38, v38
	v_add_f32_e32 v35, 1.0, v35
	v_exp_f32_e32 v39, v39
	v_rcp_f32_e32 v35, v35
	v_fma_f32 v62, -v38, v38, 1.0
	v_lshlrev_b32_e32 v34, 2, v34
	v_add_f32_e32 v39, 1.0, v39
	v_max_f32_e32 v62, 0, v62
	v_add_u32_e32 v40, 0, v34
	v_mul_f32_e32 v35, 0xc1000000, v35
	v_rcp_f32_e32 v39, v39
	v_sqrt_f32_e32 v62, v62
	ds_read_b32 v63, v54
	ds_write_b32 v40, v38 offset:62720
	v_add_f32_e32 v38, v32, v56
	v_mul_f32_e32 v35, v37, v35
	v_mul_f32_e32 v38, 0xbfb8aa3b, v38
	v_mul_f32_e32 v35, 0x3fb8aa3b, v35
	v_exp_f32_e32 v38, v38
	v_exp_f32_e32 v35, v35
	v_mul_f32_e32 v39, v39, v62
	s_waitcnt lgkmcnt(1)
	v_mul_f32_e32 v39, v63, v39
	v_add_u32_e32 v34, s0, v34
	ds_write_b32 v34, v39
	v_add_f32_e32 v34, 1.0, v38
	v_fma_f32 v38, -v35, v35, 1.0
	v_max_f32_e32 v38, 0, v38
	v_rcp_f32_e32 v34, v34
	v_sqrt_f32_e32 v38, v38
	ds_read_b32 v39, v54 offset:260
	v_mfma_f32_16x16x32_bf16 v[42:45], v[42:45], v[8:11], 0
	v_mul_f32_e32 v34, v34, v38
	v_or_b32_e32 v38, 0x200, v64
	s_waitcnt lgkmcnt(0)
	v_mul_f32_e32 v34, v34, v39
	v_add_f32_e32 v39, v33, v41
	v_mul_f32_e32 v39, 0xbfb8aa3b, v39
	v_exp_f32_e32 v39, v39
	v_add_u32_e32 v40, 0, v38
	ds_write_b32 v40, v35 offset:62720
	v_add_u32_e32 v35, s0, v38
	v_add_f32_e32 v38, 1.0, v39
	v_rcp_f32_e32 v38, v38
	v_add_f32_e32 v39, v32, v57
	v_mul_f32_e32 v39, 0xbfb8aa3b, v39
	v_mfma_f32_16x16x32_bf16 v[50:53], v[46:49], v[4:7], v[50:53]
	v_exp_f32_e32 v39, v39
	v_mul_f32_e32 v38, 0xc1000000, v38
	v_mul_f32_e32 v38, v37, v38
	v_mul_f32_e32 v38, 0x3fb8aa3b, v38
	v_exp_f32_e32 v55, v38
	ds_write_b32 v35, v34
	v_add_f32_e32 v34, 1.0, v39
	v_mfma_f32_16x16x32_bf16 v[38:41], v[46:49], v[0:3], v[42:45]
	v_fma_f32 v35, -v55, v55, 1.0
	v_max_f32_e32 v35, 0, v35
	v_rcp_f32_e32 v34, v34
	v_add_f32_e32 v42, v33, v50
	v_mul_f32_e32 v42, 0xbfb8aa3b, v42
	v_exp_f32_e32 v42, v42
	v_sqrt_f32_e32 v35, v35
	ds_read_b32 v56, v54 offset:520
	v_add_f32_e32 v38, v32, v38
	v_add_f32_e32 v42, 1.0, v42
	v_rcp_f32_e32 v42, v42
	v_mul_f32_e32 v38, 0xbfb8aa3b, v38
	v_exp_f32_e32 v38, v38
	v_mul_f32_e32 v34, v34, v35
	v_mul_f32_e32 v42, 0xc1000000, v42
	v_mul_f32_e32 v42, v37, v42
	v_mul_f32_e32 v42, 0x3fb8aa3b, v42
	v_exp_f32_e32 v46, v42
	v_or_b32_e32 v35, 0x300, v64
	s_waitcnt lgkmcnt(0)
; __device__ __forceinline__ float fexp(float x) { return __expf(x); }
; __device__ __forceinline__ float sigm(float x) { return frcp(1.f + fexp(-x)); }
; __device__ void rg_tile(unsigned char* lds, const Params& p, int l, int b, int ck, int hh, bool outmode) {
;     ...
; #pragma unroll
;     for (int tf = 0; tf < 4; ++tf)
; #pragma unroll
;       for (int jj = 0; jj < 4; ++jj) {
;         const int tt = tf * 16 + lg * 4 + jj;
;         const float r = sigm(ar[tf][jj] + br);
;         const float ig = sigm(ai[tf][jj] + bi);
;         const float la = -8.0f * r * sp;
;         const float a = fexp(la);
;         const float bq = __builtin_amdgcn_sqrtf(fmaxf(1.f - a * a, 0.f)) * ig * XR[tt * 65 + j];
;         AA[(d * 64 + tt) * 64 + j] = a;
;         BQ[(d * 64 + tt) * 64 + j] = bq;
;       }
	v_mul_f32_e32 v34, v34, v56
	v_add_u32_e32 v43, 0, v35
	v_add_u32_e32 v35, s0, v35
	ds_write_b32 v35, v34
	v_fma_f32 v35, -v46, v46, 1.0
	ds_write_b32 v43, v55 offset:62720
	v_add_f32_e32 v34, 1.0, v38
	v_max_f32_e32 v35, 0, v35
	v_rcp_f32_e32 v34, v34
	v_sqrt_f32_e32 v35, v35
	ds_read_b32 v38, v54 offset:3900
	v_add_f32_e32 v39, v32, v39
	v_mul_f32_e32 v39, 0xbfb8aa3b, v39
	v_mul_f32_e32 v34, v34, v35
	v_exp_f32_e32 v39, v39
	s_waitcnt lgkmcnt(0)
	v_mul_f32_e32 v34, v34, v38
	v_add_f32_e32 v38, v33, v51
	v_mul_f32_e32 v38, 0xbfb8aa3b, v38
	v_exp_f32_e32 v38, v38
	v_or_b32_e32 v35, 0x1000, v64
	v_add_u32_e32 v47, 0, v35
	v_add_u32_e32 v35, s0, v35
	v_add_f32_e32 v38, 1.0, v38
	v_rcp_f32_e32 v38, v38
	ds_write_b32 v35, v34
	ds_write_b32 v47, v46 offset:62720
	v_add_f32_e32 v34, 1.0, v39
	v_mul_f32_e32 v38, 0xc1000000, v38
	v_mul_f32_e32 v38, v37, v38
	v_mul_f32_e32 v38, 0x3fb8aa3b, v38
	v_exp_f32_e32 v38, v38
	v_rcp_f32_e32 v34, v34
	ds_read_b32 v39, v54 offset:4160
	v_mfma_f32_16x16x32_bf16 v[42:45], v[58:61], v[12:15], 0
	v_fma_f32 v35, -v38, v38, 1.0
	v_max_f32_e32 v35, 0, v35
	v_sqrt_f32_e32 v35, v35
	v_mfma_f32_16x16x32_bf16 v[42:45], v[24:27], v[4:7], v[42:45]
	v_mul_f32_e32 v34, v34, v35
	s_waitcnt lgkmcnt(0)
	v_mul_f32_e32 v34, v34, v39
	v_add_f32_e32 v39, v33, v52
	v_mul_f32_e32 v39, 0xbfb8aa3b, v39
	v_exp_f32_e32 v39, v39
	v_or_b32_e32 v35, 0x1100, v64
	v_add_u32_e32 v50, 0, v35
	ds_write_b32 v50, v38 offset:62720
	v_add_f32_e32 v38, 1.0, v39
	v_rcp_f32_e32 v38, v38
	v_add_f32_e32 v39, v32, v40
	v_mul_f32_e32 v39, 0xbfb8aa3b, v39
	v_exp_f32_e32 v39, v39
	v_mul_f32_e32 v38, 0xc1000000, v38
	v_mul_f32_e32 v38, v37, v38
	v_mul_f32_e32 v38, 0x3fb8aa3b, v38
	v_exp_f32_e32 v38, v38
	v_add_u32_e32 v35, s0, v35
	ds_write_b32 v35, v34
	v_add_f32_e32 v34, 1.0, v39
	v_fma_f32 v35, -v38, v38, 1.0
	v_max_f32_e32 v35, 0, v35
	v_rcp_f32_e32 v34, v34
	v_sqrt_f32_e32 v35, v35
	ds_read_b32 v39, v54 offset:4420
	v_mfma_f32_16x16x32_bf16 v[46:49], v[58:61], v[8:11], 0
	v_mul_f32_e32 v34, v34, v35
	v_or_b32_e32 v35, 0x1200, v64
	s_waitcnt lgkmcnt(0)
	v_mul_f32_e32 v34, v34, v39
	v_add_f32_e32 v39, v33, v53
	v_mul_f32_e32 v39, 0xbfb8aa3b, v39
	v_exp_f32_e32 v39, v39
	v_add_u32_e32 v40, 0, v35
	ds_write_b32 v40, v38 offset:62720
	v_add_u32_e32 v35, s0, v35
	v_add_f32_e32 v38, 1.0, v39
	v_rcp_f32_e32 v38, v38
	v_add_f32_e32 v39, v32, v41
	v_mul_f32_e32 v39, 0xbfb8aa3b, v39
	v_exp_f32_e32 v39, v39
	v_mul_f32_e32 v38, 0xc1000000, v38
	v_mul_f32_e32 v38, v37, v38
	v_mul_f32_e32 v38, 0x3fb8aa3b, v38
	v_exp_f32_e32 v38, v38
	ds_write_b32 v35, v34
	v_add_f32_e32 v34, 1.0, v39
	v_rcp_f32_e32 v34, v34
	v_fma_f32 v35, -v38, v38, 1.0
	v_max_f32_e32 v35, 0, v35
	v_sqrt_f32_e32 v35, v35
	ds_read_b32 v39, v54 offset:4680
	v_mfma_f32_16x16x32_bf16 v[24:27], v[24:27], v[0:3], v[46:49]
	v_mul_f32_e32 v34, v34, v35
	v_or_b32_e32 v35, 0x1300, v64
	s_waitcnt lgkmcnt(0)
	v_mul_f32_e32 v34, v34, v39
	v_add_f32_e32 v39, v33, v42
	v_mul_f32_e32 v39, 0xbfb8aa3b, v39
	v_exp_f32_e32 v39, v39
	v_add_u32_e32 v40, 0, v35
	ds_write_b32 v40, v38 offset:62720
	v_add_f32_e32 v24, v32, v24
	v_add_f32_e32 v38, 1.0, v39
	v_rcp_f32_e32 v38, v38
	v_mul_f32_e32 v24, 0xbfb8aa3b, v24
	v_exp_f32_e32 v24, v24
	v_add_u32_e32 v35, s0, v35
	v_mul_f32_e32 v38, 0xc1000000, v38
	v_mul_f32_e32 v38, v37, v38
	v_mul_f32_e32 v38, 0x3fb8aa3b, v38
	v_exp_f32_e32 v38, v38
	ds_write_b32 v35, v34
	v_add_f32_e32 v24, 1.0, v24
	v_rcp_f32_e32 v24, v24
	v_fma_f32 v34, -v38, v38, 1.0
	v_max_f32_e32 v34, 0, v34
	v_sqrt_f32_e32 v34, v34
	ds_read_b32 v35, v54 offset:8060
	v_mfma_f32_16x16x32_bf16 v[12:15], v[20:23], v[12:15], 0
	v_add_f32_e32 v25, v32, v25
	v_mul_f32_e32 v24, v24, v34
	v_mul_f32_e32 v25, 0xbfb8aa3b, v25
	s_waitcnt lgkmcnt(0)
	v_mul_f32_e32 v24, v24, v35
	v_add_f32_e32 v35, v33, v43
	v_mul_f32_e32 v35, 0xbfb8aa3b, v35
	v_exp_f32_e32 v35, v35
	v_mfma_f32_16x16x32_bf16 v[8:11], v[20:23], v[8:11], 0
	v_add_f32_e32 v22, v33, v44
	v_mul_f32_e32 v22, 0xbfb8aa3b, v22
	v_add_f32_e32 v35, 1.0, v35
	v_rcp_f32_e32 v35, v35
	v_exp_f32_e32 v22, v22
	v_exp_f32_e32 v25, v25
	v_or_b32_e32 v34, 0x2000, v64
	v_mul_f32_e32 v35, 0xc1000000, v35
	v_mul_f32_e32 v35, v37, v35
	v_mul_f32_e32 v35, 0x3fb8aa3b, v35
	v_exp_f32_e32 v35, v35
	v_add_f32_e32 v22, 1.0, v22
	v_rcp_f32_e32 v22, v22
	v_mfma_f32_16x16x32_bf16 v[4:7], v[16:19], v[4:7], v[12:15]
	v_add_u32_e32 v39, 0, v34
	v_add_u32_e32 v34, s0, v34
	ds_write_b32 v34, v24
	v_add_f32_e32 v14, v33, v45
	v_mul_f32_e32 v14, 0xbfb8aa3b, v14
	v_add_f32_e32 v24, 1.0, v25
	v_fma_f32 v25, -v35, v35, 1.0
	v_exp_f32_e32 v14, v14
	ds_write_b32 v39, v38 offset:62720
	v_max_f32_e32 v25, 0, v25
	v_or_b32_e32 v21, 0x2100, v64
	v_mul_f32_e32 v22, 0xc1000000, v22
	v_rcp_f32_e32 v24, v24
	v_sqrt_f32_e32 v25, v25
	ds_read_b32 v34, v54 offset:8320
	v_add_u32_e32 v23, 0, v21
	v_mul_f32_e32 v22, v37, v22
	ds_write_b32 v23, v35 offset:62720
	v_add_f32_e32 v23, v32, v26
	v_mul_f32_e32 v22, 0x3fb8aa3b, v22
	v_mul_f32_e32 v23, 0xbfb8aa3b, v23
	v_exp_f32_e32 v22, v22
	v_add_f32_e32 v14, 1.0, v14
	v_exp_f32_e32 v23, v23
	v_rcp_f32_e32 v14, v14
	v_mul_f32_e32 v20, v24, v25
	v_add_f32_e32 v4, v33, v4
	s_waitcnt lgkmcnt(1)
	v_mul_f32_e32 v20, v20, v34
	v_add_u32_e32 v21, s0, v21
	v_mul_f32_e32 v4, 0xbfb8aa3b, v4
	ds_write_b32 v21, v20
	v_fma_f32 v21, -v22, v22, 1.0
	v_exp_f32_e32 v4, v4
	v_add_f32_e32 v20, 1.0, v23
	v_max_f32_e32 v21, 0, v21
	v_or_b32_e32 v13, 0x2200, v64
	v_mul_f32_e32 v14, 0xc1000000, v14
	v_rcp_f32_e32 v20, v20
	v_sqrt_f32_e32 v21, v21
	ds_read_b32 v23, v54 offset:8580
	v_add_u32_e32 v15, 0, v13
	v_mul_f32_e32 v14, v37, v14
	ds_write_b32 v15, v22 offset:62720
	v_add_f32_e32 v15, v32, v27
	v_mul_f32_e32 v14, 0x3fb8aa3b, v14
	v_mul_f32_e32 v15, 0xbfb8aa3b, v15
	v_exp_f32_e32 v14, v14
	v_add_f32_e32 v4, 1.0, v4
	v_exp_f32_e32 v15, v15
	v_rcp_f32_e32 v4, v4
	v_mul_f32_e32 v12, v20, v21
	s_waitcnt lgkmcnt(1)
; __device__ __forceinline__ float fexp(float x) { return __expf(x); }
; __device__ __forceinline__ float sigm(float x) { return frcp(1.f + fexp(-x)); }
; __device__ void rg_tile(unsigned char* lds, const Params& p, int l, int b, int ck, int hh, bool outmode) {
;     ...
;     for (int tf = 0; tf < 4; ++tf)
; #pragma unroll
;       for (int jj = 0; jj < 4; ++jj) {
;         const int tt = tf * 16 + lg * 4 + jj;
;         const float r = sigm(ar[tf][jj] + br);
;         const float ig = sigm(ai[tf][jj] + bi);
;         const float la = -8.0f * r * sp;
;         const float a = fexp(la);
;         const float bq = __builtin_amdgcn_sqrtf(fmaxf(1.f - a * a, 0.f)) * ig * XR[tt * 65 + j];
;         AA[(d * 64 + tt) * 64 + j] = a;
;         BQ[(d * 64 + tt) * 64 + j] = bq;
;       }
;   }
;   __syncthreads();
;   {
;     float* SEG = XR;
;     const int seg = tid >> 7, d = (tid >> 6) & 1, j = tid & 63;
;     const int ch = hh * 64 + j;
;     const size_t ci = ((size_t)(b * 36 + ck) * 2 + d) * 256 + ch;
;     float H = 0.f, Ap = 1.f;
; #pragma unroll
;     for (int q = 0; q < 16; ++q) {
;       const int pos = seg * 16 + q;
;       const int tt = d == 0 ? pos : 63 - pos;
;       const float a = AA[(d * 64 + tt) * 64 + j];
;       H = a * H + BQ[(d * 64 + tt) * 64 + j];
	v_mul_f32_e32 v12, v12, v23
	v_add_u32_e32 v13, s0, v13
	v_mfma_f32_16x16x32_bf16 v[0:3], v[16:19], v[0:3], v[8:11]
	v_add_f32_e32 v5, v33, v5
	ds_write_b32 v13, v12
	v_fma_f32 v13, -v14, v14, 1.0
	v_mul_f32_e32 v5, 0xbfb8aa3b, v5
	v_add_f32_e32 v12, 1.0, v15
	v_max_f32_e32 v13, 0, v13
	v_mul_f32_e32 v4, 0xc1000000, v4
	v_exp_f32_e32 v5, v5
	v_rcp_f32_e32 v12, v12
	v_sqrt_f32_e32 v13, v13
	ds_read_b32 v15, v54 offset:8840
	v_mul_f32_e32 v4, v37, v4
	v_add_f32_e32 v0, v32, v0
	v_mul_f32_e32 v4, 0x3fb8aa3b, v4
	v_mul_f32_e32 v0, 0xbfb8aa3b, v0
	v_exp_f32_e32 v4, v4
	v_exp_f32_e32 v0, v0
	v_add_f32_e32 v5, 1.0, v5
	v_mul_f32_e32 v8, v12, v13
	v_or_b32_e32 v9, 0x2300, v64
	v_rcp_f32_e32 v5, v5
	s_waitcnt lgkmcnt(0)
	v_mul_f32_e32 v8, v8, v15
	v_add_u32_e32 v10, 0, v9
	v_add_u32_e32 v9, s0, v9
	ds_write_b32 v9, v8
	v_fma_f32 v8, -v4, v4, 1.0
	ds_write_b32 v10, v14 offset:62720
	v_add_f32_e32 v0, 1.0, v0
	v_max_f32_e32 v8, 0, v8
	v_rcp_f32_e32 v0, v0
	v_sqrt_f32_e32 v8, v8
	ds_read_b32 v9, v54 offset:12220
	v_mul_f32_e32 v5, 0xc1000000, v5
	v_add_f32_e32 v1, v32, v1
	v_mul_f32_e32 v5, v37, v5
	v_mul_f32_e32 v1, 0xbfb8aa3b, v1
	v_mul_f32_e32 v5, 0x3fb8aa3b, v5
	v_exp_f32_e32 v1, v1
	v_exp_f32_e32 v5, v5
	v_mul_f32_e32 v0, v0, v8
	v_or_b32_e32 v8, 0x3000, v64
	s_waitcnt lgkmcnt(0)
	v_mul_f32_e32 v0, v0, v9
	v_add_u32_e32 v9, 0, v8
	ds_write_b32 v9, v4 offset:62720
	v_add_u32_e32 v4, s0, v8
	ds_write_b32 v4, v0
	v_add_f32_e32 v0, 1.0, v1
	v_fma_f32 v1, -v5, v5, 1.0
	v_max_f32_e32 v1, 0, v1
	v_rcp_f32_e32 v0, v0
	v_sqrt_f32_e32 v1, v1
	ds_read_b32 v4, v54 offset:12480
	v_add_f32_e32 v2, v32, v2
	v_mul_f32_e32 v2, 0xbfb8aa3b, v2
	v_mul_f32_e32 v0, v0, v1
	v_exp_f32_e32 v2, v2
	s_waitcnt lgkmcnt(0)
	v_mul_f32_e32 v0, v0, v4
	v_add_f32_e32 v4, v33, v6
	v_mul_f32_e32 v4, 0xbfb8aa3b, v4
	v_exp_f32_e32 v4, v4
	v_or_b32_e32 v1, 0x3100, v64
	v_add_u32_e32 v6, 0, v1
	v_add_u32_e32 v1, s0, v1
	v_add_f32_e32 v4, 1.0, v4
	v_rcp_f32_e32 v4, v4
	ds_write_b32 v1, v0
	ds_write_b32 v6, v5 offset:62720
	v_add_f32_e32 v0, 1.0, v2
	v_mul_f32_e32 v4, 0xc1000000, v4
	v_mul_f32_e32 v4, v37, v4
	v_mul_f32_e32 v4, 0x3fb8aa3b, v4
	v_exp_f32_e32 v4, v4
	v_rcp_f32_e32 v0, v0
	ds_read_b32 v2, v54 offset:12740
	v_add_f32_e32 v3, v32, v3
	v_fma_f32 v1, -v4, v4, 1.0
	v_max_f32_e32 v1, 0, v1
	v_sqrt_f32_e32 v1, v1
	v_mul_f32_e32 v3, 0xbfb8aa3b, v3
	v_exp_f32_e32 v3, v3
	v_lshlrev_b32_e32 v15, 4, v36
	v_mul_f32_e32 v0, v0, v1
	s_waitcnt lgkmcnt(0)
	v_mul_f32_e32 v0, v0, v2
	v_add_f32_e32 v2, v33, v7
	v_mul_f32_e32 v2, 0xbfb8aa3b, v2
	v_exp_f32_e32 v2, v2
	v_or_b32_e32 v1, 0x3200, v64
	v_add_u32_e32 v5, 0, v1
	v_add_u32_e32 v1, s0, v1
	v_add_f32_e32 v2, 1.0, v2
	v_rcp_f32_e32 v2, v2
	ds_write_b32 v1, v0
	ds_write_b32 v5, v4 offset:62720
	v_add_f32_e32 v0, 1.0, v3
	v_mul_f32_e32 v2, 0xc1000000, v2
	v_mul_f32_e32 v2, v37, v2
	v_mul_f32_e32 v2, 0x3fb8aa3b, v2
	v_exp_f32_e32 v2, v2
	v_rcp_f32_e32 v0, v0
	ds_read_b32 v3, v54 offset:13000
	v_and_b32_e32 v18, 1, v28
	v_fma_f32 v1, -v2, v2, 1.0
	v_max_f32_e32 v1, 0, v1
	v_sqrt_f32_e32 v1, v1
	v_or_b32_e32 v4, 2, v15
	v_or_b32_e32 v6, 3, v15
	v_cmp_eq_u32_e32 vcc, 0, v18
	v_mul_f32_e32 v0, v0, v1
	v_or_b32_e32 v1, 0x3300, v64
	s_waitcnt lgkmcnt(0)
	v_mul_f32_e32 v0, v0, v3
	v_add_u32_e32 v3, 0, v1
	ds_write_b32 v3, v2 offset:62720
	v_add_u32_e32 v1, s0, v1
	v_or_b32_e32 v2, 1, v15
	ds_write_b32 v1, v0
	v_sub_u32_e32 v0, 63, v15
	v_sub_u32_e32 v3, 63, v2
	v_sub_u32_e32 v5, 63, v4
	v_sub_u32_e32 v7, 63, v6
	v_cndmask_b32_e32 v0, v0, v15, vcc
	v_cndmask_b32_e32 v2, v3, v2, vcc
	v_cndmask_b32_e32 v4, v5, v4, vcc
	v_cndmask_b32_e32 v6, v7, v6, vcc
	v_lshl_or_b32 v19, v18, 12, v31
	v_lshlrev_b32_e32 v0, 6, v0
	v_lshlrev_b32_e32 v2, 6, v2
	v_lshlrev_b32_e32 v4, 6, v4
	v_lshlrev_b32_e32 v6, 6, v6
	v_add_lshl_u32 v0, v0, v19, 2
	v_add_lshl_u32 v2, v2, v19, 2
	v_add_lshl_u32 v4, v4, v19, 2
	v_add_lshl_u32 v6, v6, v19, 2
	v_add_u32_e32 v1, 0, v0
	v_add_u32_e32 v0, s0, v0
	v_add_u32_e32 v3, 0, v2
	v_add_u32_e32 v2, s0, v2
	v_add_u32_e32 v5, 0, v4
	v_add_u32_e32 v7, 0, v6
	s_waitcnt lgkmcnt(0)
	s_barrier
; __device__ void rg_tile(unsigned char* lds, const Params& p, int l, int b, int ck, int hh, bool outmode) {
;     ...
;   {
;     float* SEG = XR;
;     const int seg = tid >> 7, d = (tid >> 6) & 1, j = tid & 63;
;     const int ch = hh * 64 + j;
;     const size_t ci = ((size_t)(b * 36 + ck) * 2 + d) * 256 + ch;
;     float H = 0.f, Ap = 1.f;
; #pragma unroll
;     for (int q = 0; q < 16; ++q) {
;       const int pos = seg * 16 + q;
;       const int tt = d == 0 ? pos : 63 - pos;
;       const float a = AA[(d * 64 + tt) * 64 + j];
;       H = a * H + BQ[(d * 64 + tt) * 64 + j];
;       Ap *= a;
;     }
;     SEG[((seg * 2 + d) * 64 + j) * 2 + 0] = Ap;
;     SEG[((seg * 2 + d) * 64 + j) * 2 + 1] = H;
;     __syncthreads();
;     if (!outmode) {
;       if (seg == 0) {
;         float Ht = 0.f, At = 1.f;
; #pragma unroll
;         for (int sgi = 0; sgi < 4; ++sgi) {
;           const float as = SEG[((sgi * 2 + d) * 64 + j) * 2 + 0], hs = SEG[((sgi * 2 + d) * 64 + j) * 2 + 1];
;           Ht = as * Ht + hs;
;           At *= as;
;         }
;         agg[ci * 2 + 0] = At;
;         agg[ci * 2 + 1] = Ht;
;       }
	v_add_u32_e32 v4, s0, v4
	v_add_u32_e32 v6, s0, v6
	ds_read_b32 v1, v1 offset:62720
	ds_read_b32 v8, v0
	ds_read_b32 v3, v3 offset:62720
	ds_read_b32 v9, v2
	ds_read_b32 v0, v5 offset:62720
	ds_read_b32 v5, v4
	ds_read_b32 v2, v7 offset:62720
	ds_read_b32 v7, v6
	s_waitcnt lgkmcnt(6)
	v_fmac_f32_e32 v8, 0, v1
	v_or_b32_e32 v6, 5, v15
	s_waitcnt lgkmcnt(4)
	v_fmac_f32_e32 v9, v8, v3
	v_sub_u32_e32 v8, 63, v6
	v_cndmask_b32_e32 v6, v8, v6, vcc
	v_lshlrev_b32_e32 v6, 6, v6
	v_add_lshl_u32 v6, v6, v19, 2
	s_waitcnt lgkmcnt(2)
	v_fmac_f32_e32 v5, v9, v0
	v_add_u32_e32 v8, 0, v6
	v_add_u32_e32 v9, s0, v6
	v_or_b32_e32 v6, 6, v15
	v_sub_u32_e32 v10, 63, v6
	v_cndmask_b32_e32 v6, v10, v6, vcc
	v_lshlrev_b32_e32 v6, 6, v6
	v_add_lshl_u32 v6, v6, v19, 2
	v_mul_f32_e32 v4, v1, v3
	v_or_b32_e32 v1, 4, v15
	v_add_u32_e32 v10, 0, v6
	v_add_u32_e32 v11, s0, v6
	v_or_b32_e32 v6, 7, v15
	v_sub_u32_e32 v3, 63, v1
	v_sub_u32_e32 v12, 63, v6
	v_cndmask_b32_e32 v1, v3, v1, vcc
	v_cndmask_b32_e32 v6, v12, v6, vcc
	v_lshlrev_b32_e32 v1, 6, v1
	v_lshlrev_b32_e32 v6, 6, v6
	v_add_lshl_u32 v1, v1, v19, 2
	v_add_lshl_u32 v6, v6, v19, 2
	v_add_u32_e32 v3, 0, v1
	v_add_u32_e32 v1, s0, v1
	v_add_u32_e32 v12, 0, v6
	v_add_u32_e32 v13, s0, v6
	ds_read_b32 v6, v3 offset:62720
	ds_read_b32 v1, v1
	ds_read_b32 v8, v8 offset:62720
	ds_read_b32 v3, v9
	ds_read_b32 v10, v10 offset:62720
	ds_read_b32 v9, v11
	ds_read_b32 v12, v12 offset:62720
	ds_read_b32 v16, v13
	s_waitcnt lgkmcnt(8)
	v_fmac_f32_e32 v7, v5, v2
	v_or_b32_e32 v5, 9, v15
	s_waitcnt lgkmcnt(6)
	v_fmac_f32_e32 v1, v7, v6
	v_sub_u32_e32 v7, 63, v5
	v_cndmask_b32_e32 v5, v7, v5, vcc
	s_waitcnt lgkmcnt(4)
	v_fmac_f32_e32 v3, v1, v8
	v_lshlrev_b32_e32 v5, 6, v5
	s_waitcnt lgkmcnt(2)
	v_fmac_f32_e32 v9, v3, v10
	v_add_lshl_u32 v5, v5, v19, 2
	s_waitcnt lgkmcnt(0)
	v_fmac_f32_e32 v16, v9, v12
	v_add_u32_e32 v7, 0, v5
	v_add_u32_e32 v9, s0, v5
	v_or_b32_e32 v5, 10, v15
	v_sub_u32_e32 v11, 63, v5
	v_cndmask_b32_e32 v5, v11, v5, vcc
	v_lshlrev_b32_e32 v5, 6, v5
	v_or_b32_e32 v1, 8, v15
	v_add_lshl_u32 v5, v5, v19, 2
	v_sub_u32_e32 v3, 63, v1
	v_add_u32_e32 v11, 0, v5
	v_add_u32_e32 v13, s0, v5
	v_or_b32_e32 v5, 11, v15
	v_cndmask_b32_e32 v1, v3, v1, vcc
	v_sub_u32_e32 v14, 63, v5
	v_lshlrev_b32_e32 v1, 6, v1
	v_cndmask_b32_e32 v5, v14, v5, vcc
	v_add_lshl_u32 v1, v1, v19, 2
	v_lshlrev_b32_e32 v5, 6, v5
	v_add_u32_e32 v3, 0, v1
	v_add_u32_e32 v1, s0, v1
	v_add_lshl_u32 v5, v5, v19, 2
	v_add_u32_e32 v17, 0, v5
	v_add_u32_e32 v20, s0, v5
	ds_read_b32 v14, v3 offset:62720
	ds_read_b32 v5, v1
	ds_read_b32 v1, v7 offset:62720
	ds_read_b32 v3, v9
	ds_read_b32 v7, v11 offset:62720
	ds_read_b32 v9, v13
	ds_read_b32 v11, v17 offset:62720
	ds_read_b32 v13, v20
	s_waitcnt lgkmcnt(6)
	v_fmac_f32_e32 v5, v16, v14
	v_mul_f32_e32 v16, v4, v0
	v_mul_f32_e32 v16, v16, v2
	s_waitcnt lgkmcnt(4)
	v_pk_fma_f32 v[2:3], v[4:5], v[0:1], v[2:3]
	v_or_b32_e32 v0, 12, v15
	v_mov_b32_e32 v17, v3
	s_waitcnt lgkmcnt(3)
	v_pk_mul_f32 v[2:3], v[16:17], v[6:7]
	s_waitcnt lgkmcnt(2)
	v_pk_fma_f32 v[4:5], v[16:17], v[6:7], v[8:9]
	v_pk_mul_f32 v[2:3], v[2:3], v[8:9]
	v_or_b32_e32 v8, 13, v15
	v_sub_u32_e32 v9, 63, v8
	v_cndmask_b32_e32 v8, v9, v8, vcc
	v_or_b32_e32 v9, 14, v15
	v_sub_u32_e32 v17, 63, v9
	v_cndmask_b32_e32 v9, v17, v9, vcc
	v_lshlrev_b32_e32 v9, 6, v9
	v_add_lshl_u32 v9, v9, v19, 2
	v_sub_u32_e32 v6, 63, v0
	v_add_u32_e32 v20, 0, v9
	v_add_u32_e32 v22, s0, v9
	v_or_b32_e32 v9, 15, v15
	v_cndmask_b32_e32 v0, v6, v0, vcc
	v_sub_u32_e32 v15, 63, v9
	v_lshlrev_b32_e32 v0, 6, v0
	v_cndmask_b32_e32 v9, v15, v9, vcc
	v_add_lshl_u32 v0, v0, v19, 2
	v_lshlrev_b32_e32 v8, 6, v8
	v_lshlrev_b32_e32 v9, 6, v9
	v_mov_b32_e32 v4, v2
	v_add_u32_e32 v6, 0, v0
	v_add_u32_e32 v0, s0, v0
	v_add_lshl_u32 v8, v8, v19, 2
	v_add_lshl_u32 v9, v9, v19, 2
	s_waitcnt lgkmcnt(1)
	v_pk_mul_f32 v[2:3], v[2:3], v[10:11]
	v_add_u32_e32 v16, 0, v8
	v_add_u32_e32 v8, s0, v8
	v_add_u32_e32 v24, 0, v9
	v_add_u32_e32 v26, s0, v9
	ds_read_b32 v15, v6 offset:62720
	ds_read_b32 v9, v0
	ds_read_b32 v17, v16 offset:62720
	ds_read_b32 v19, v8
	ds_read_b32 v21, v20 offset:62720
	ds_read_b32 v23, v22
	ds_read_b32 v25, v24 offset:62720
	ds_read_b32 v27, v26
	v_and_b32_e32 v0, 0x1fffff80, v29
	v_lshlrev_b32_e32 v6, 6, v18
	s_waitcnt lgkmcnt(8)
	v_pk_mul_f32 v[2:3], v[2:3], v[12:13]
	v_pk_fma_f32 v[4:5], v[4:5], v[10:11], v[12:13]
	v_or3_b32 v0, v6, v0, v31
	v_mov_b32_e32 v3, v5
	v_lshl_add_u32 v6, v0, 3, 0
	s_waitcnt lgkmcnt(7)
	v_pk_mul_f32 v[4:5], v[2:3], v[14:15]
	v_mov_b32_e32 v0, v1
	v_mov_b32_e32 v8, v1
	v_pk_mul_f32 v[0:1], v[4:5], v[0:1]
	s_waitcnt lgkmcnt(6)
	v_pk_fma_f32 v[2:3], v[2:3], v[14:15], v[8:9]
	v_mov_b32_e32 v4, v7
	v_mov_b32_e32 v2, v0
	v_mov_b32_e32 v16, v7
	v_pk_mul_f32 v[0:1], v[0:1], v[4:5]
	v_mov_b32_e32 v4, v11
	v_mov_b32_e32 v18, v11
	v_pk_mul_f32 v[0:1], v[0:1], v[4:5]
	s_waitcnt lgkmcnt(4)
	v_pk_fma_f32 v[2:3], v[2:3], v[16:17], v[18:19]
	v_mov_b32_e32 v20, v15
	v_mov_b32_e32 v1, v3
	s_waitcnt lgkmcnt(3)
	v_pk_mul_f32 v[2:3], v[0:1], v[20:21]
	v_mov_b32_e32 v4, v17
	v_mov_b32_e32 v22, v17
	v_pk_mul_f32 v[2:3], v[2:3], v[4:5]
	s_waitcnt lgkmcnt(2)
	v_pk_fma_f32 v[0:1], v[0:1], v[20:21], v[22:23]
	v_mov_b32_e32 v4, v21
	v_mov_b32_e32 v0, v2
	v_mov_b32_e32 v24, v21
	v_pk_mul_f32 v[2:3], v[2:3], v[4:5]
	s_waitcnt lgkmcnt(1)
	v_mov_b32_e32 v4, v25
	v_mov_b32_e32 v26, v25
	v_pk_mul_f32 v[2:3], v[2:3], v[4:5]
	s_waitcnt lgkmcnt(0)
	v_pk_fma_f32 v[0:1], v[0:1], v[24:25], v[26:27]
	v_cmp_gt_u32_e32 vcc, s91, v29
	v_mov_b32_e32 v3, v1
	ds_write_b64 v6, v[2:3]
	s_waitcnt lgkmcnt(0)
	s_barrier
	s_and_saveexec_b64 s[0:1], vcc
	s_cbranch_execz .LBB0_329
	v_lshlrev_b32_e32 v0, 3, v29
	v_add_u32_e32 v4, 0, v0
	ds_read2st64_b64 v[0:3], v4 offset1:2
	ds_read2st64_b64 v[4:7], v4 offset0:4 offset1:6
	s_mul_i32 s3, s3, 36
	s_add_i32 s3, s3, s2
	s_lshl_b32 s2, s3, 9
	s_waitcnt lgkmcnt(1)
	v_fma_f32 v1, 0, v0, v1
	v_fmac_f32_e32 v3, v1, v2
	v_lshlrev_b32_e32 v8, 8, v28
	v_mul_f32_e32 v0, v0, v2
	s_waitcnt lgkmcnt(0)
	v_fma_f32 v1, v3, v4, v5
	v_mov_b32_e32 v5, v6
	v_or3_b32 v192, v8, s2, v30
	v_readlane_b32 s2, v251, 56
	v_pk_mul_f32 v[8:9], v[0:1], v[4:5]
	v_readlane_b32 s3, v251, 57
	v_pk_mul_f32 v[8:9], v[8:9], v[6:7]
	v_pk_fma_f32 v[0:1], v[0:1], v[4:5], v[6:7]
	v_lshl_add_u64 v[2:3], v[192:193], 3, s[2:3]
	v_mov_b32_e32 v9, v1
	global_store_dwordx2 v[2:3], v[8:9], off

; __device__ __forceinline__ bf16_t f2bf(float f) { return (bf16_t)(pack2(f, 0.f) & 0xffffu); }
; __device__ __forceinline__ float bf2f(bf16_t h) { return __uint_as_float(((unsigned)h) << 16); }
; __device__ void rg_tile(unsigned char* lds, const Params& p, int l, int b, int ck, int hh, bool outmode) {
;     ...
;   float car_pre = 0.f, gp_pre[8];
;   {
;     const int d_ = (tid >> 6) & 1, j_ = tid & 63;
;     if (outmode) {
;       car_pre = car[((size_t)(b * 36 + ck) * 2 + d_) * 256 + hh * 64 + j_];
; #pragma unroll
;       for (int q = 0; q < 8; ++q) gp_pre[q] = bf2f(z[(size_t)(rowbase + t0 + w * 8 + q) * ZS + 2816 + 256 + hh * 64 + lane]);
;     } else {
; #pragma unroll
;       for (int q = 0; q < 8; ++q) gp_pre[q] = 0.f;
;     }
;   }
;   const int chm_ = hh * 64 + (w & 3) * 16 + lr, dm_ = w >> 2;
;   const float br = p.in[22][(size_t)l * 1024 + (dm_ * 2 + 0) * 256 + chm_];
;   const float bi = p.in[22][(size_t)l * 1024 + (dm_ * 2 + 1) * 256 + chm_];
;   const float lam_ = p.in[23][(size_t)l * 512 + dm_ * 256 + chm_];
;   {
;     const int i = tid & 63, tq = tid >> 6;
;     const int ch = hh * 64 + i;
;     const float* wc = p.in[20] + (size_t)l * 4 * 256 + ch;
;     const float w0 = wc[0], w1 = wc[256], w2 = wc[512], w3 = wc[768];
; #pragma unroll
;     for (int ii = 0; ii < 8; ++ii) {
;       const int tt = tq * 8 + ii;
;       const int tp = t0 + tt;
;       const int tm1 = tp - 1 >= 0 ? tp - 1 : 0, tp1 = tp + 1 < L ? tp + 1 : L - 1, tp2 = tp + 2 < L ? tp + 2 : L - 1;
;       const float z0 = bf2f(z[(size_t)(rowbase + tm1) * ZS + 2816 + ch]);
;       const float z1 = bf2f(z[(size_t)(rowbase + tp) * ZS + 2816 + ch]);
;       const float z2 = bf2f(z[(size_t)(rowbase + tp1) * ZS + 2816 + ch]);
;       const float z3 = bf2f(z[(size_t)(rowbase + tp2) * ZS + 2816 + ch]);
;       float xr = w1 * z1;
;       xr += (tp - 1 >= 0 ? w0 : 0.f) * z0;
;       xr += (tp + 1 < L ? w2 : 0.f) * z2;
;       xr += (tp + 2 < L ? w3 : 0.f) * z3;
;       XR[tt * 65 + i] = xr;
;       XB[tt * 72 + i] = f2bf(xr);
;     }
.LBB0_708:
	s_and_b64 vcc, exec, s[0:1]
	s_cbranch_vccz .LBB0_812
	s_sub_i32 s0, s13, s30
	s_ashr_i32 s2, s0, 2
	s_abs_i32 s2, s2
	v_readlane_b32 s3, v254, 14
	s_mul_hi_u32 s3, s2, s3
	v_readlane_b32 s4, v254, 11
	s_mul_i32 s3, s3, s4
	s_sub_i32 s2, s2, s3
	s_and_b32 s1, s13, 3
	s_sub_i32 s3, s2, s4
	s_cmp_ge_u32 s2, s4
	s_cselect_b32 s2, s3, s2
	s_sub_i32 s3, s2, s4
	s_cmp_ge_u32 s2, s4
	s_cselect_b32 s2, s3, s2
	s_ashr_i32 s3, s0, 31
	s_xor_b32 s2, s2, s3
	s_sub_i32 s2, s2, s3
	v_readlane_b32 s4, v254, 22
	s_add_i32 s4, s2, s4
	s_abs_i32 s0, s0
	v_readlane_b32 s2, v254, 16
	s_mul_hi_u32 s2, s0, s2
	v_readlane_b32 s7, v254, 15
	s_mul_i32 s5, s2, s7
	s_sub_i32 s0, s0, s5
	s_add_i32 s5, s2, 1
	s_sub_i32 s6, s0, s7
	s_cmp_ge_u32 s0, s7
	s_cselect_b32 s2, s5, s2
	s_cselect_b32 s0, s6, s0
	s_add_i32 s5, s2, 1
	s_cmp_ge_u32 s0, s7
	s_cselect_b32 s0, s5, s2
	s_xor_b32 s0, s0, s3
	s_sub_i32 s5, s0, s3
	s_lshl_b32 s2, s4, 6
	s_lshl_b32 s0, s5, 8
	s_add_i32 s3, s2, 0xffffff00
	s_add_i32 s6, s0, 0x4000
	s_lshl_b32 s7, s5, 11
	s_cmp_lt_i32 s4, 4
	s_movk_i32 s0, 0x800
	s_mul_i32 s5, s5, 36
	s_cselect_b32 s0, 0x100, s0
	s_cselect_b32 s3, s2, s3
	s_cselect_b32 s2, s6, s7
	s_add_i32 s4, s5, s4
	v_mov_b32_e32 v52, v195
	v_readfirstlane_b32 s44, v195
	s_mov_b32 s47, s0
	s_mov_b32 s48, s2
	s_mov_b32 s49, s3
	s_lshl_b32 s50, s1, 7
	s_lshr_b32 s44, s44, 6
	s_lshl_b32 s45, s44, 3
	s_add_i32 s45, s45, s49
	s_add_i32 s46, s47, -1
	s_addk_i32 s50, 0x1600
	v_and_b32_e32 v185, 63, v195
	v_lshl_add_u32 v180, v185, 1, s50
	v_readlane_b32 s52, v254, 3
	v_readlane_b32 s53, v254, 4
	s_lshl_b32 s51, s1, 8
	v_lshl_add_u32 v181, v185, 2, s51
	s_nop 4
	global_load_dword v165, v181, s[52:53]
	global_load_dword v166, v181, s[52:53] offset:1024
	global_load_dword v167, v181, s[52:53] offset:2048
	global_load_dword v168, v181, s[52:53] offset:3072
	s_add_i32 s54, s45, s48
	s_mul_i32 s54, s54, 0x1a00
	v_add_u32_e32 v181, s54, v180
	s_add_i32 s55, s45, -1
	s_max_i32 s55, s55, 0
	s_add_i32 s55, s55, s48
	s_mul_i32 s55, s55, 0x1a00
	v_add_u32_e32 v184, s55, v180
	global_load_ushort v154, v184, s[88:89]
	global_load_ushort v155, v181, s[88:89]
	global_load_ushort v49, v181, s[88:89] offset:512
	v_add_u32_e32 v181, 0x1a00, v181
	global_load_ushort v156, v181, s[88:89]
	global_load_ushort v50, v181, s[88:89] offset:512
	v_add_u32_e32 v181, 0x1a00, v181
	global_load_ushort v157, v181, s[88:89]
	global_load_ushort v41, v181, s[88:89] offset:512
	v_add_u32_e32 v181, 0x1a00, v181
	global_load_ushort v158, v181, s[88:89]
	global_load_ushort v36, v181, s[88:89] offset:512
	v_add_u32_e32 v181, 0x1a00, v181
	global_load_ushort v159, v181, s[88:89]
	global_load_ushort v34, v181, s[88:89] offset:512
	v_add_u32_e32 v181, 0x1a00, v181
	global_load_ushort v160, v181, s[88:89]
	global_load_ushort v35, v181, s[88:89] offset:512
	v_add_u32_e32 v181, 0x1a00, v181
	global_load_ushort v161, v181, s[88:89]
	global_load_ushort v31, v181, s[88:89] offset:512
	v_add_u32_e32 v181, 0x1a00, v181
	global_load_ushort v162, v181, s[88:89]
	global_load_ushort v42, v181, s[88:89] offset:512
	s_add_i32 s55, s45, 8
	s_min_i32 s55, s55, s46
	s_add_i32 s55, s55, s48
	s_mul_i32 s55, s55, 0x1a00
	v_add_u32_e32 v184, s55, v180
	global_load_ushort v163, v184, s[88:89]
	s_add_i32 s55, s45, 9
	s_min_i32 s55, s55, s46
	s_add_i32 s55, s55, s48
	s_mul_i32 s55, s55, 0x1a00
	v_add_u32_e32 v184, s55, v180
	global_load_ushort v164, v184, s[88:89]
	s_mul_i32 s55, s44, 0x820
	v_lshl_add_u32 v182, v185, 2, s55
	s_mul_i32 s55, s44, 0x480
	v_lshl_add_u32 v183, v185, 1, s55
	s_ashr_i32 s5, s4, 31
	s_lshl_b32 s7, s1, 6
	v_ashrrev_i32_e32 v47, 6, v52
	s_lshl_b64 s[4:5], s[4:5], 11
	v_readlane_b32 s8, v252, 11
	v_and_b32_e32 v48, 1, v47
	v_readlane_b32 s9, v252, 12
	s_add_u32 s4, s8, s4
	s_addc_u32 s5, s9, s5
	v_lshlrev_b32_e32 v192, 10, v48
	v_and_b32_e32 v29, 63, v52
	v_lshl_add_u64 v[0:1], s[4:5], 0, v[192:193]
	s_lshl_b32 s96, s1, 8
	v_lshl_add_u64 v[0:1], v[0:1], 0, s[96:97]
	v_lshlrev_b32_e32 v192, 2, v29
	s_add_i32 s4, s3, s2
	v_lshlrev_b32_e32 v12, 3, v47
	v_lshl_add_u64 v[2:3], v[0:1], 0, v[192:193]
	v_add_u32_e32 v28, s4, v12
	v_mov_b64_e32 v[0:1], s[88:89]
	s_lshl_b32 s96, s1, 7
	s_movk_i32 s10, 0x1000
	s_nop 0
	s_nop 0
	global_load_dword v51, v[2:3], off
	s_add_i32 s6, s2, -1
	v_or_b32_e32 v7, s7, v29
	v_lshlrev_b32_e32 v32, 1, v7
	v_mov_b32_e32 v33, v193
	v_lshlrev_b32_e32 v39, 2, v7
	s_add_i32 s5, s0, -1
	s_nop 0
	s_nop 0
	s_nop 0
	s_nop 0
	v_and_b32_e32 v6, 15, v52
	s_nop 0
	v_lshlrev_b32_e32 v2, 4, v47
	v_ashrrev_i32_e32 v56, 8, v52
	v_and_or_b32 v55, v2, 48, v6
	v_lshlrev_b32_e32 v2, 9, v56
	v_readlane_b32 s8, v254, 12
	v_lshl_or_b32 v7, v56, 1, 1
	v_or_b32_e32 v4, s7, v55
	v_ashrrev_i32_e32 v3, 31, v2
	v_readlane_b32 s9, v254, 13
	v_lshlrev_b32_e32 v16, 8, v7
	v_lshlrev_b32_e32 v4, 2, v4
	v_lshl_add_u64 v[2:3], v[2:3], 2, s[8:9]
	v_mov_b32_e32 v5, v193
	v_ashrrev_i32_e32 v17, 31, v16
	v_lshl_add_u64 v[2:3], v[2:3], 0, v[4:5]
	v_lshl_add_u64 v[16:17], v[16:17], 2, s[8:9]
	v_lshl_add_u64 v[16:17], v[16:17], 0, v[4:5]
	global_load_dword v54, v[2:3], off
	global_load_dword v53, v[16:17], off
	v_and_b32_e32 v2, 0xffffff00, v52
	v_readlane_b32 s8, v254, 1
	v_ashrrev_i32_e32 v3, 31, v2
	v_readlane_b32 s9, v254, 2
	v_or_b32_e32 v37, 1, v12
	v_add_u32_e32 v30, 0, v192
	v_lshl_add_u64 v[2:3], v[2:3], 2, s[8:9]
	v_lshl_add_u64 v[2:3], v[2:3], 0, v[4:5]
	global_load_dword v16, v[2:3], off
	s_nop 0
	s_nop 0
	v_or_b32_e32 v38, 2, v12
	s_nop 0
	v_or_b32_e32 v40, 3, v12
	s_nop 0
	s_nop 0
	s_nop 0
	s_nop 0
	s_nop 0
	s_nop 0
	v_or_b32_e32 v43, 4, v12
	s_nop 0
	s_movk_i32 s12, 0x104
	s_movk_i32 s11, 0x90
	s_nop 0
	v_or_b32_e32 v44, 5, v12
; __device__ __forceinline__ bf16_t f2bf(float f) { return (bf16_t)(pack2(f, 0.f) & 0xffffu); }
; __device__ __forceinline__ float bf2f(bf16_t h) { return __uint_as_float(((unsigned)h) << 16); }
; __device__ void rg_tile(unsigned char* lds, const Params& p, int l, int b, int ck, int hh, bool outmode) {
;     ...
;   {
;     const int i = tid & 63, tq = tid >> 6;
;     const int ch = hh * 64 + i;
;     const float* wc = p.in[20] + (size_t)l * 4 * 256 + ch;
;     const float w0 = wc[0], w1 = wc[256], w2 = wc[512], w3 = wc[768];
; #pragma unroll
;     for (int ii = 0; ii < 8; ++ii) {
;       const int tt = tq * 8 + ii;
;       const int tp = t0 + tt;
;       const int tm1 = tp - 1 >= 0 ? tp - 1 : 0, tp1 = tp + 1 < L ? tp + 1 : L - 1, tp2 = tp + 2 < L ? tp + 2 : L - 1;
;       const float z0 = bf2f(z[(size_t)(rowbase + tm1) * ZS + 2816 + ch]);
;       const float z1 = bf2f(z[(size_t)(rowbase + tp) * ZS + 2816 + ch]);
;       const float z2 = bf2f(z[(size_t)(rowbase + tp1) * ZS + 2816 + ch]);
;       const float z3 = bf2f(z[(size_t)(rowbase + tp2) * ZS + 2816 + ch]);
;       float xr = w1 * z1;
;       xr += (tp - 1 >= 0 ? w0 : 0.f) * z0;
;       xr += (tp + 1 < L ? w2 : 0.f) * z2;
;       xr += (tp + 2 < L ? w3 : 0.f) * z3;
;       XR[tt * 65 + i] = xr;
;       XB[tt * 72 + i] = f2bf(xr);
;     }
;     const bf16_t* rgw = (const bf16_t*)(p.ws + OFF_RGW);
; #pragma unroll
;     for (int q = 0; q < 4; ++q) {
;       const int id = tid + 512 * q;
;       const int row = id >> 3, kc = id & 7;
;       *(uint4*)(WT + row * 72 + kc * 8) = *(const uint4*)(rgw + ((size_t)((l * 4 + (row >> 6)) * 4 + hh)) * 4096 + (row & 63) * 64 + kc * 8);
;     }
;   }
	v_or_b32_e32 v45, 6, v12
	v_add_u32_e32 v68, s3, v45
	s_nop 0
	v_add_u32_e32 v69, 2, v68
	v_min_i32_e32 v26, s5, v69
	v_or_b32_e32 v46, 7, v12
	v_add_u32_e32 v13, s2, v26
	v_add_u32_e32 v70, s3, v46
	v_mad_i64_i32 v[26:27], s[8:9], v13, s92, v[0:1]
	v_max_i32_e32 v12, 1, v70
	v_add_u32_e32 v12, s6, v12
	v_mad_u64_u32 v[12:13], s[6:7], v12, s92, v[0:1]
	v_lshl_add_u64 v[12:13], v[12:13], 0, v[32:33]
	v_add_u32_e32 v58, s2, v70
	v_add_co_u32_e32 v12, vcc, s10, v12
	v_mad_i64_i32 v[58:59], s[6:7], v58, s92, v[0:1]
	v_addc_co_u32_e32 v13, vcc, 0, v13, vcc
	v_ashrrev_i32_e32 v80, 3, v52
	s_nop 0
	global_load_ushort v78, v[12:13], off offset:1536
	v_readlane_b32 s2, v254, 5
	v_lshlrev_b32_e32 v12, 4, v52
	v_ashrrev_i32_e32 v33, 7, v52
	s_or_b32 s1, s1, s2
	v_and_b32_e32 v26, 0x70, v12
	v_and_b32_e32 v12, -4, v33
	v_add_u32_e32 v12, s1, v12
	v_ashrrev_i32_e32 v13, 31, v12
	v_readlane_b32 s2, v251, 22
	v_lshlrev_b64 v[12:13], 13, v[12:13]
	v_readlane_b32 s3, v251, 23
	v_lshlrev_b32_e32 v14, 7, v80
	v_and_b32_e32 v14, 0x1f80, v14
	v_lshl_add_u64 v[12:13], s[2:3], 0, v[12:13]
	v_mov_b32_e32 v15, v193
	v_lshl_add_u64 v[12:13], v[12:13], 0, v[14:15]
	v_mov_b32_e32 v27, v193
	v_lshl_add_u64 v[12:13], v[12:13], 0, v[26:27]
	s_nop 0
	global_load_dwordx4 v[12:15], v[12:13], off
	v_add_u32_e32 v0, 0x200, v52
	v_ashrrev_i32_e32 v82, 3, v0
	v_ashrrev_i32_e32 v0, 7, v0
	v_and_b32_e32 v0, -4, v0
	v_add_u32_e32 v0, s1, v0
	v_ashrrev_i32_e32 v1, 31, v0
	v_lshlrev_b64 v[0:1], 13, v[0:1]
	v_lshlrev_b32_e32 v18, 7, v82
	v_lshl_add_u64 v[0:1], s[2:3], 0, v[0:1]
	v_and_b32_e32 v18, 0x1f80, v18
	v_mov_b32_e32 v19, v193
	v_lshl_add_u64 v[0:1], v[0:1], 0, v[18:19]
	v_add_u32_e32 v18, 0x400, v52
	v_ashrrev_i32_e32 v83, 3, v18
	v_ashrrev_i32_e32 v18, 7, v18
	v_and_b32_e32 v18, -4, v18
	v_add_u32_e32 v18, s1, v18
	v_ashrrev_i32_e32 v19, 31, v18
	v_lshlrev_b64 v[18:19], 13, v[18:19]
	v_lshlrev_b32_e32 v20, 7, v83
	v_lshl_add_u64 v[18:19], s[2:3], 0, v[18:19]
	v_and_b32_e32 v20, 0x1f80, v20
	v_mov_b32_e32 v21, v193
	v_lshl_add_u64 v[18:19], v[18:19], 0, v[20:21]
	v_lshl_add_u64 v[0:1], v[0:1], 0, v[26:27]
	v_lshl_add_u64 v[22:23], v[18:19], 0, v[26:27]
	global_load_dwordx4 v[18:21], v[0:1], off
	s_nop 0
	global_load_dwordx4 v[22:25], v[22:23], off
	v_add_u32_e32 v0, 0x600, v52
	v_ashrrev_i32_e32 v84, 3, v0
	v_ashrrev_i32_e32 v0, 7, v0
	v_and_b32_e32 v0, -4, v0
	v_add_u32_e32 v0, s1, v0
	v_ashrrev_i32_e32 v1, 31, v0
	v_lshlrev_b64 v[0:1], 13, v[0:1]
	v_lshlrev_b32_e32 v58, 7, v84
	v_lshl_add_u64 v[0:1], s[2:3], 0, v[0:1]
	v_and_b32_e32 v58, 0x1f80, v58
	v_mov_b32_e32 v59, v193
	v_lshl_add_u64 v[0:1], v[0:1], 0, v[58:59]
	v_lshl_add_u64 v[0:1], v[0:1], 0, v[26:27]
	global_load_dwordx4 v[58:61], v[0:1], off
	s_waitcnt vmcnt(0)
	v_lshlrev_b32_e32 v1, 16, v78
	s_nop 0
	s_nop 0
	v_add_u32_e32 v0, 0, v26
	v_mad_u64_u32 v[2:3], s[0:1], v80, s11, v[0:1]
	ds_write_b128 v2, v[12:15] offset:25856
	v_mad_u64_u32 v[2:3], s[0:1], v82, s11, v[0:1]
	ds_write_b128 v2, v[18:21] offset:25856
	v_mad_u64_u32 v[2:3], s[0:1], v83, s11, v[0:1]
	v_mad_u64_u32 v[0:1], s[0:1], v84, s11, v[0:1]
	ds_write_b128 v2, v[22:25] offset:25856
	ds_write_b128 v0, v[58:61] offset:25856
	v_and_b32_e32 v0, 48, v52
	v_add_u32_e32 v0, 0, v0
	v_mad_u32_u24 v17, v6, s11, v0
	s_waitcnt vmcnt(0)
	v_lshlrev_b32_e32 v154, 16, v154
	v_lshlrev_b32_e32 v155, 16, v155
	v_lshlrev_b32_e32 v156, 16, v156
	v_lshlrev_b32_e32 v157, 16, v157
	v_lshlrev_b32_e32 v158, 16, v158
	v_lshlrev_b32_e32 v159, 16, v159
	v_lshlrev_b32_e32 v160, 16, v160
	v_lshlrev_b32_e32 v161, 16, v161
	v_lshlrev_b32_e32 v162, 16, v162
	v_lshlrev_b32_e32 v163, 16, v163
	v_lshlrev_b32_e32 v164, 16, v164
	s_cmp_ge_i32 s45, 1
	s_cselect_b64 s[56:57], -1, 0
	s_add_i32 s55, s45, 8
	s_cmp_lt_i32 s55, s47
	s_cselect_b64 s[58:59], -1, 0
	v_cndmask_b32_e64 v169, 0, v165, s[56:57]
	v_cndmask_b32_e64 v170, 0, v167, s[58:59]
	v_cndmask_b32_e64 v171, 0, v168, s[58:59]
	v_mul_f32_e32 v172, v166, v155
	v_fmac_f32_e32 v172, v169, v154
	v_fmac_f32_e32 v172, v167, v156
	v_fmac_f32_e32 v172, v168, v157
	v_mul_f32_e32 v173, v166, v156
	v_fmac_f32_e32 v173, v165, v155
	v_fmac_f32_e32 v173, v167, v157
	v_fmac_f32_e32 v173, v168, v158
	v_mul_f32_e32 v174, v166, v157
	v_fmac_f32_e32 v174, v165, v156
	v_fmac_f32_e32 v174, v167, v158
	v_fmac_f32_e32 v174, v168, v159
	v_mul_f32_e32 v175, v166, v158
	v_fmac_f32_e32 v175, v165, v157
	v_fmac_f32_e32 v175, v167, v159
	v_fmac_f32_e32 v175, v168, v160
	v_mul_f32_e32 v176, v166, v159
	v_fmac_f32_e32 v176, v165, v158
	v_fmac_f32_e32 v176, v167, v160
	v_fmac_f32_e32 v176, v168, v161
	v_mul_f32_e32 v177, v166, v160
	v_fmac_f32_e32 v177, v165, v159
	v_fmac_f32_e32 v177, v167, v161
	v_fmac_f32_e32 v177, v168, v162
	v_mul_f32_e32 v178, v166, v161
	v_fmac_f32_e32 v178, v165, v160
	v_fmac_f32_e32 v178, v167, v162
	v_fmac_f32_e32 v178, v171, v163
	v_mul_f32_e32 v179, v166, v162
	v_fmac_f32_e32 v179, v165, v161
	v_fmac_f32_e32 v179, v170, v163
	v_fmac_f32_e32 v179, v171, v164
	v_cvt_pk_bf16_f32 v184, v172, v172
	ds_write_b32 v182, v172
	ds_write_b16 v183, v184 offset:16640
	v_cvt_pk_bf16_f32 v184, v173, v173
	ds_write_b32 v182, v173 offset:260
	ds_write_b16 v183, v184 offset:16784
	v_cvt_pk_bf16_f32 v184, v174, v174
	ds_write_b32 v182, v174 offset:520
	ds_write_b16 v183, v184 offset:16928
	v_cvt_pk_bf16_f32 v184, v175, v175
	ds_write_b32 v182, v175 offset:780
	ds_write_b16 v183, v184 offset:17072
	v_cvt_pk_bf16_f32 v184, v176, v176
	ds_write_b32 v182, v176 offset:1040
	ds_write_b16 v183, v184 offset:17216
	v_cvt_pk_bf16_f32 v184, v177, v177
	ds_write_b32 v182, v177 offset:1300
	ds_write_b16 v183, v184 offset:17360
	v_cvt_pk_bf16_f32 v184, v178, v178
	ds_write_b32 v182, v178 offset:1560
	ds_write_b16 v183, v184 offset:17504
	v_cvt_pk_bf16_f32 v184, v179, v179
	ds_write_b32 v182, v179 offset:1820
	ds_write_b16 v183, v184 offset:17648
	s_waitcnt lgkmcnt(0)
	s_barrier
; __device__ __forceinline__ float fexp(float x) { return __expf(x); }
; __device__ __forceinline__ float sigm(float x) { return frcp(1.f + fexp(-x)); }
; __device__ __forceinline__ float softplusf(float x) { return fmaxf(x, 0.f) + __logf(1.f + fexp(-fabsf(x))); }
; __device__ void rg_tile(unsigned char* lds, const Params& p, int l, int b, int ck, int hh, bool outmode) {
;     ...
;   {
;     const int d = w >> 2, jf = w & 3;
;     f32x4 ar[4], ai[4];
; #pragma unroll
;     for (int i = 0; i < 4; ++i) { ar[i] = (f32x4){0.f, 0.f, 0.f, 0.f}; ai[i] = (f32x4){0.f, 0.f, 0.f, 0.f}; }
; #pragma unroll
;     for (int ks = 0; ks < 2; ++ks) {
;       const bf16x8 wr = ldfrag(WT + ((d * 2 + 0) * 64 + jf * 16 + lr) * 72 + ks * 32 + lg * 8);
;       const bf16x8 wi = ldfrag(WT + ((d * 2 + 1) * 64 + jf * 16 + lr) * 72 + ks * 32 + lg * 8);
; #pragma unroll
;       for (int tf = 0; tf < 4; ++tf) {
;         const bf16x8 xf = ldfrag(XB + (tf * 16 + lr) * 72 + ks * 32 + lg * 8);
;         ar[tf] = mfma16(xf, wr, ar[tf]);
;         ai[tf] = mfma16(xf, wi, ai[tf]);
;       }
;     }
;     const int j = jf * 16 + lr;
;     const int ch = hh * 64 + j;
;     const float sp = softplusf(-lam_);
; #pragma unroll
;     for (int tf = 0; tf < 4; ++tf)
; #pragma unroll
;       for (int jj = 0; jj < 4; ++jj) {
;         const int tt = tf * 16 + lg * 4 + jj;
;         const float r = sigm(ar[tf][jj] + br);
;         const float ig = sigm(ai[tf][jj] + bi);
;         const float la = -8.0f * r * sp;
;         const float a = fexp(la);
;         const float bq = __builtin_amdgcn_sqrtf(fmaxf(1.f - a * a, 0.f)) * ig * XR[tt * 65 + j];
;         AA[(d * 64 + tt) * 64 + j] = a;
;         BQ[(d * 64 + tt) * 64 + j] = bq;
;       }
	ds_read_b128 v[18:21], v17 offset:16640
	v_lshl_or_b32 v1, v56, 7, v55
	v_mad_u64_u32 v[2:3], s[0:1], v1, s11, v[0:1]
	v_lshl_or_b32 v1, v7, 6, v55
	ds_read_b128 v[12:15], v2 offset:25856
	v_mad_u64_u32 v[0:1], s[0:1], v1, s11, v[0:1]
	ds_read_b128 v[4:7], v2 offset:25920
	ds_read_b128 v[22:25], v17 offset:16704
	ds_read_b128 v[8:11], v0 offset:25856
	ds_read_b128 v[0:3], v0 offset:25920
	s_mov_b32 s0, 0xbfb8aa3b
	v_mul_f32_e64 v26, |v16|, s0
	s_waitcnt lgkmcnt(4)
	v_mfma_f32_16x16x32_bf16 v[58:61], v[18:21], v[12:15], 0
	v_exp_f32_e32 v26, v26
	s_mov_b32 s0, 0x800000
	v_max_f32_e64 v16, -v16, -v16
	s_waitcnt lgkmcnt(1)
	v_mfma_f32_16x16x32_bf16 v[18:21], v[18:21], v[8:11], 0
	v_max_f32_e32 v16, 0, v16
	v_bfe_u32 v82, v52, 4, 2
	ds_read_b128 v[62:65], v17 offset:18944
	ds_read_b128 v[66:69], v17 offset:19008
	s_waitcnt lgkmcnt(2)
	v_mfma_f32_16x16x32_bf16 v[74:77], v[22:25], v[0:3], v[18:21]
	v_lshlrev_b32_e32 v56, 12, v56
	v_and_b32_e32 v52, 0x1fffff80, v52
	s_nop 0
	v_add_f32_e32 v18, 1.0, v26
	v_cmp_gt_f32_e32 vcc, s0, v18
	v_mfma_f32_16x16x32_bf16 v[58:61], v[22:25], v[4:7], v[58:61]
	s_mov_b32 s0, 0x3f317217
	v_cndmask_b32_e64 v19, 0, 32, vcc
	v_ldexp_f32 v18, v18, v19
	v_log_f32_e32 v18, v18
	v_mov_b32_e32 v20, 0x41b17218
	v_cndmask_b32_e32 v20, 0, v20, vcc
	s_nop 1
	v_add_f32_e32 v59, v54, v59
	v_mul_f32_e32 v19, 0x3f317217, v18
	v_fma_f32 v19, v18, s0, -v19
	v_fmac_f32_e32 v19, 0x3377d1cf, v18
	s_mov_b32 s0, 0x7f800000
	v_fmac_f32_e32 v19, 0x3f317217, v18
	v_cmp_lt_f32_e64 s[0:1], |v18|, s0
	ds_read_b128 v[78:81], v17 offset:21248
	ds_read_b128 v[24:27], v17 offset:21312
	v_cndmask_b32_e64 v18, v18, v19, s[0:1]
	v_add_f32_e32 v19, v54, v58
	v_mul_f32_e32 v19, 0xbfb8aa3b, v19
	v_exp_f32_e32 v19, v19
	v_sub_f32_e32 v18, v18, v20
	v_add_f32_e32 v57, v16, v18
	v_add_f32_e32 v18, v53, v74
	v_add_f32_e32 v16, 1.0, v19
	v_rcp_f32_e32 v16, v16
	v_mul_f32_e32 v18, 0xbfb8aa3b, v18
	v_exp_f32_e32 v18, v18
	v_lshl_add_u32 v74, v55, 2, 0
	v_mul_f32_e32 v16, 0xc1000000, v16
	v_mul_f32_e32 v16, v57, v16
	v_mul_f32_e32 v16, 0x3fb8aa3b, v16
	v_exp_f32_e32 v58, v16
	v_add_f32_e32 v16, 1.0, v18
	v_rcp_f32_e32 v83, v16
	s_movk_i32 s0, 0x410
	v_fma_f32 v16, -v58, v58, 1.0
	v_max_f32_e32 v16, 0, v16
	v_sqrt_f32_e32 v84, v16
	v_mad_u32_u24 v16, v82, s0, v74
	ds_read_b32 v85, v16
	ds_read_b128 v[20:23], v17 offset:23552
	ds_read_b128 v[16:19], v17 offset:23616
	v_mul_f32_e32 v59, 0xbfb8aa3b, v59
	v_mul_f32_e32 v83, v83, v84
	v_lshlrev_b32_e32 v84, 8, v82
	v_or3_b32 v84, v84, v56, v55
	v_exp_f32_e32 v59, v59
	v_lshlrev_b32_e32 v84, 2, v84
	s_waitcnt lgkmcnt(2)
	v_mul_f32_e32 v83, v85, v83
	v_add_u32_e32 v85, 0, v84
	v_readlane_b32 s0, v253, 37
	ds_write_b32 v85, v58 offset:62720
	v_mfma_f32_16x16x32_bf16 v[70:73], v[62:65], v[12:15], 0
	v_add_u32_e32 v58, s0, v84
	ds_write_b32 v58, v83
	v_add_f32_e32 v58, 1.0, v59
	v_add_f32_e32 v59, v53, v75
	v_lshl_or_b32 v75, v82, 2, 1
	v_rcp_f32_e32 v58, v58
	v_mad_u32_u24 v74, v75, s12, v74
	v_lshlrev_b32_e32 v75, 6, v75
	v_or3_b32 v55, v75, v56, v55
	v_add_f32_e32 v56, v54, v60
	v_mul_f32_e32 v56, 0xbfb8aa3b, v56
	v_exp_f32_e32 v56, v56
	v_mul_f32_e32 v58, 0xc1000000, v58
	v_mul_f32_e32 v58, v57, v58
	v_mul_f32_e32 v58, 0x3fb8aa3b, v58
	v_mul_f32_e32 v59, 0xbfb8aa3b, v59
	v_exp_f32_e32 v58, v58
	v_add_f32_e32 v56, 1.0, v56
	v_exp_f32_e32 v59, v59
	v_rcp_f32_e32 v56, v56
	v_fma_f32 v82, -v58, v58, 1.0
	v_lshlrev_b32_e32 v55, 2, v55
	v_add_f32_e32 v59, 1.0, v59
	v_max_f32_e32 v82, 0, v82
	v_add_u32_e32 v60, 0, v55
	v_mul_f32_e32 v56, 0xc1000000, v56
	v_rcp_f32_e32 v59, v59
	v_sqrt_f32_e32 v82, v82
	ds_read_b32 v83, v74
	ds_write_b32 v60, v58 offset:62720
	v_add_f32_e32 v58, v53, v76
	v_mul_f32_e32 v56, v57, v56
	v_mul_f32_e32 v58, 0xbfb8aa3b, v58
	v_mul_f32_e32 v56, 0x3fb8aa3b, v56
	v_exp_f32_e32 v58, v58
	v_exp_f32_e32 v56, v56
	v_mul_f32_e32 v59, v59, v82
	s_waitcnt lgkmcnt(1)
	v_mul_f32_e32 v59, v83, v59
	v_add_u32_e32 v55, s0, v55
	ds_write_b32 v55, v59
	v_add_f32_e32 v55, 1.0, v58
	v_fma_f32 v58, -v56, v56, 1.0
	v_max_f32_e32 v58, 0, v58
	v_rcp_f32_e32 v55, v55
	v_sqrt_f32_e32 v58, v58
	ds_read_b32 v59, v74 offset:260
	v_mfma_f32_16x16x32_bf16 v[62:65], v[62:65], v[8:11], 0
	v_cmp_eq_u32_e32 vcc, 0, v48
	v_mul_f32_e32 v55, v55, v58
	v_or_b32_e32 v58, 0x200, v84
	s_waitcnt lgkmcnt(0)
	v_mul_f32_e32 v55, v55, v59
	v_add_f32_e32 v59, v54, v61
	v_mul_f32_e32 v59, 0xbfb8aa3b, v59
	v_exp_f32_e32 v59, v59
	v_add_u32_e32 v60, 0, v58
	ds_write_b32 v60, v56 offset:62720
	v_add_u32_e32 v56, s0, v58
	v_add_f32_e32 v58, 1.0, v59
	v_rcp_f32_e32 v58, v58
	v_add_f32_e32 v59, v53, v77
	v_mul_f32_e32 v59, 0xbfb8aa3b, v59
	v_mfma_f32_16x16x32_bf16 v[70:73], v[66:69], v[4:7], v[70:73]
	v_exp_f32_e32 v59, v59
	v_mul_f32_e32 v58, 0xc1000000, v58
	v_mul_f32_e32 v58, v57, v58
	v_mul_f32_e32 v58, 0x3fb8aa3b, v58
	v_exp_f32_e32 v75, v58
	ds_write_b32 v56, v55
	v_add_f32_e32 v55, 1.0, v59
	v_mfma_f32_16x16x32_bf16 v[58:61], v[66:69], v[0:3], v[62:65]
	v_fma_f32 v56, -v75, v75, 1.0
	v_max_f32_e32 v56, 0, v56
	v_rcp_f32_e32 v55, v55
	v_add_f32_e32 v62, v54, v70
	v_mul_f32_e32 v62, 0xbfb8aa3b, v62
	v_exp_f32_e32 v62, v62
	v_sqrt_f32_e32 v56, v56
	ds_read_b32 v76, v74 offset:520
	v_add_f32_e32 v58, v53, v58
	v_add_f32_e32 v62, 1.0, v62
	v_rcp_f32_e32 v62, v62
	v_mul_f32_e32 v58, 0xbfb8aa3b, v58
	v_exp_f32_e32 v58, v58
	v_mul_f32_e32 v55, v55, v56
	v_mul_f32_e32 v62, 0xc1000000, v62
	v_mul_f32_e32 v62, v57, v62
	v_mul_f32_e32 v62, 0x3fb8aa3b, v62
	v_exp_f32_e32 v66, v62
	v_or_b32_e32 v56, 0x300, v84
	s_waitcnt lgkmcnt(0)
; __device__ __forceinline__ float fexp(float x) { return __expf(x); }
; __device__ __forceinline__ float sigm(float x) { return frcp(1.f + fexp(-x)); }
; __device__ void rg_tile(unsigned char* lds, const Params& p, int l, int b, int ck, int hh, bool outmode) {
;     ...
;     for (int tf = 0; tf < 4; ++tf)
; #pragma unroll
;       for (int jj = 0; jj < 4; ++jj) {
;         const int tt = tf * 16 + lg * 4 + jj;
;         const float r = sigm(ar[tf][jj] + br);
;         const float ig = sigm(ai[tf][jj] + bi);
;         const float la = -8.0f * r * sp;
;         const float a = fexp(la);
;         const float bq = __builtin_amdgcn_sqrtf(fmaxf(1.f - a * a, 0.f)) * ig * XR[tt * 65 + j];
;         AA[(d * 64 + tt) * 64 + j] = a;
;         BQ[(d * 64 + tt) * 64 + j] = bq;
;       }
	v_mul_f32_e32 v55, v55, v76
	v_add_u32_e32 v63, 0, v56
	v_add_u32_e32 v56, s0, v56
	ds_write_b32 v56, v55
	v_fma_f32 v56, -v66, v66, 1.0
	ds_write_b32 v63, v75 offset:62720
	v_add_f32_e32 v55, 1.0, v58
	v_max_f32_e32 v56, 0, v56
	v_rcp_f32_e32 v55, v55
	v_sqrt_f32_e32 v56, v56
	ds_read_b32 v58, v74 offset:3900
	v_add_f32_e32 v59, v53, v59
	v_mul_f32_e32 v59, 0xbfb8aa3b, v59
	v_mul_f32_e32 v55, v55, v56
	v_exp_f32_e32 v59, v59
	s_waitcnt lgkmcnt(0)
	v_mul_f32_e32 v55, v55, v58
	v_add_f32_e32 v58, v54, v71
	v_mul_f32_e32 v58, 0xbfb8aa3b, v58
	v_exp_f32_e32 v58, v58
	v_or_b32_e32 v56, 0x1000, v84
	v_add_u32_e32 v67, 0, v56
	v_add_u32_e32 v56, s0, v56
	v_add_f32_e32 v58, 1.0, v58
	v_rcp_f32_e32 v58, v58
	ds_write_b32 v56, v55
	ds_write_b32 v67, v66 offset:62720
	v_add_f32_e32 v55, 1.0, v59
	v_mul_f32_e32 v58, 0xc1000000, v58
	v_mul_f32_e32 v58, v57, v58
	v_mul_f32_e32 v58, 0x3fb8aa3b, v58
	v_exp_f32_e32 v58, v58
	v_rcp_f32_e32 v55, v55
	ds_read_b32 v59, v74 offset:4160
	v_mfma_f32_16x16x32_bf16 v[62:65], v[78:81], v[12:15], 0
	v_fma_f32 v56, -v58, v58, 1.0
	v_max_f32_e32 v56, 0, v56
	v_sqrt_f32_e32 v56, v56
	v_mfma_f32_16x16x32_bf16 v[62:65], v[24:27], v[4:7], v[62:65]
	v_mul_f32_e32 v55, v55, v56
	s_waitcnt lgkmcnt(0)
	v_mul_f32_e32 v55, v55, v59
	v_add_f32_e32 v59, v54, v72
	v_mul_f32_e32 v59, 0xbfb8aa3b, v59
	v_exp_f32_e32 v59, v59
	v_or_b32_e32 v56, 0x1100, v84
	v_add_u32_e32 v70, 0, v56
	ds_write_b32 v70, v58 offset:62720
	v_add_f32_e32 v58, 1.0, v59
	v_rcp_f32_e32 v58, v58
	v_add_f32_e32 v59, v53, v60
	v_mul_f32_e32 v59, 0xbfb8aa3b, v59
	v_exp_f32_e32 v59, v59
	v_mul_f32_e32 v58, 0xc1000000, v58
	v_mul_f32_e32 v58, v57, v58
	v_mul_f32_e32 v58, 0x3fb8aa3b, v58
	v_exp_f32_e32 v58, v58
	v_add_u32_e32 v56, s0, v56
	ds_write_b32 v56, v55
	v_add_f32_e32 v55, 1.0, v59
	v_fma_f32 v56, -v58, v58, 1.0
	v_max_f32_e32 v56, 0, v56
	v_rcp_f32_e32 v55, v55
	v_sqrt_f32_e32 v56, v56
	ds_read_b32 v59, v74 offset:4420
	v_mfma_f32_16x16x32_bf16 v[66:69], v[78:81], v[8:11], 0
	v_mul_f32_e32 v55, v55, v56
	v_or_b32_e32 v56, 0x1200, v84
	s_waitcnt lgkmcnt(0)
	v_mul_f32_e32 v55, v55, v59
	v_add_f32_e32 v59, v54, v73
	v_mul_f32_e32 v59, 0xbfb8aa3b, v59
	v_exp_f32_e32 v59, v59
	v_add_u32_e32 v60, 0, v56
	ds_write_b32 v60, v58 offset:62720
	v_add_u32_e32 v56, s0, v56
	v_add_f32_e32 v58, 1.0, v59
	v_rcp_f32_e32 v58, v58
	v_add_f32_e32 v59, v53, v61
	v_mul_f32_e32 v59, 0xbfb8aa3b, v59
	v_exp_f32_e32 v59, v59
	v_mul_f32_e32 v58, 0xc1000000, v58
	v_mul_f32_e32 v58, v57, v58
	v_mul_f32_e32 v58, 0x3fb8aa3b, v58
	v_exp_f32_e32 v58, v58
	ds_write_b32 v56, v55
	v_add_f32_e32 v55, 1.0, v59
	v_rcp_f32_e32 v55, v55
	v_fma_f32 v56, -v58, v58, 1.0
	v_max_f32_e32 v56, 0, v56
	v_sqrt_f32_e32 v56, v56
	ds_read_b32 v59, v74 offset:4680
	v_mfma_f32_16x16x32_bf16 v[24:27], v[24:27], v[0:3], v[66:69]
	v_mul_f32_e32 v55, v55, v56
	v_or_b32_e32 v56, 0x1300, v84
	s_waitcnt lgkmcnt(0)
	v_mul_f32_e32 v55, v55, v59
	v_add_f32_e32 v59, v54, v62
	v_mul_f32_e32 v59, 0xbfb8aa3b, v59
	v_exp_f32_e32 v59, v59
	v_add_u32_e32 v60, 0, v56
	ds_write_b32 v60, v58 offset:62720
	v_add_f32_e32 v24, v53, v24
	v_add_f32_e32 v58, 1.0, v59
	v_rcp_f32_e32 v58, v58
	v_mul_f32_e32 v24, 0xbfb8aa3b, v24
	v_exp_f32_e32 v24, v24
	v_add_u32_e32 v56, s0, v56
	v_mul_f32_e32 v58, 0xc1000000, v58
	v_mul_f32_e32 v58, v57, v58
	v_mul_f32_e32 v58, 0x3fb8aa3b, v58
	v_exp_f32_e32 v58, v58
	ds_write_b32 v56, v55
	v_add_f32_e32 v24, 1.0, v24
	v_rcp_f32_e32 v24, v24
	v_fma_f32 v55, -v58, v58, 1.0
	v_max_f32_e32 v55, 0, v55
	v_sqrt_f32_e32 v55, v55
	ds_read_b32 v56, v74 offset:8060
	v_mfma_f32_16x16x32_bf16 v[12:15], v[20:23], v[12:15], 0
	v_add_f32_e32 v25, v53, v25
	v_mul_f32_e32 v24, v24, v55
	v_mul_f32_e32 v25, 0xbfb8aa3b, v25
	s_waitcnt lgkmcnt(0)
	v_mul_f32_e32 v24, v24, v56
	v_add_f32_e32 v56, v54, v63
	v_mul_f32_e32 v56, 0xbfb8aa3b, v56
	v_exp_f32_e32 v56, v56
	v_mfma_f32_16x16x32_bf16 v[8:11], v[20:23], v[8:11], 0
	v_add_f32_e32 v22, v54, v64
	v_mul_f32_e32 v22, 0xbfb8aa3b, v22
	v_add_f32_e32 v56, 1.0, v56
	v_rcp_f32_e32 v56, v56
	v_exp_f32_e32 v22, v22
	v_exp_f32_e32 v25, v25
	v_or_b32_e32 v55, 0x2000, v84
	v_mul_f32_e32 v56, 0xc1000000, v56
	v_mul_f32_e32 v56, v57, v56
	v_mul_f32_e32 v56, 0x3fb8aa3b, v56
	v_exp_f32_e32 v56, v56
	v_add_f32_e32 v22, 1.0, v22
	v_rcp_f32_e32 v22, v22
	v_mfma_f32_16x16x32_bf16 v[4:7], v[16:19], v[4:7], v[12:15]
	v_add_u32_e32 v59, 0, v55
	v_add_u32_e32 v55, s0, v55
	ds_write_b32 v55, v24
	v_add_f32_e32 v14, v54, v65
	v_mul_f32_e32 v14, 0xbfb8aa3b, v14
	v_add_f32_e32 v24, 1.0, v25
	v_fma_f32 v25, -v56, v56, 1.0
	v_exp_f32_e32 v14, v14
	ds_write_b32 v59, v58 offset:62720
	v_max_f32_e32 v25, 0, v25
	v_or_b32_e32 v21, 0x2100, v84
	v_mul_f32_e32 v22, 0xc1000000, v22
	v_rcp_f32_e32 v24, v24
	v_sqrt_f32_e32 v25, v25
	ds_read_b32 v55, v74 offset:8320
	v_add_u32_e32 v23, 0, v21
	v_mul_f32_e32 v22, v57, v22
	ds_write_b32 v23, v56 offset:62720
	v_add_f32_e32 v23, v53, v26
	v_mul_f32_e32 v22, 0x3fb8aa3b, v22
	v_mul_f32_e32 v23, 0xbfb8aa3b, v23
	v_exp_f32_e32 v22, v22
	v_add_f32_e32 v14, 1.0, v14
	v_exp_f32_e32 v23, v23
	v_rcp_f32_e32 v14, v14
	v_mul_f32_e32 v20, v24, v25
	v_add_f32_e32 v4, v54, v4
	s_waitcnt lgkmcnt(1)
	v_mul_f32_e32 v20, v20, v55
	v_add_u32_e32 v21, s0, v21
	v_mul_f32_e32 v4, 0xbfb8aa3b, v4
	ds_write_b32 v21, v20
	v_fma_f32 v21, -v22, v22, 1.0
	v_exp_f32_e32 v4, v4
	v_add_f32_e32 v20, 1.0, v23
	v_max_f32_e32 v21, 0, v21
	v_or_b32_e32 v13, 0x2200, v84
	v_mul_f32_e32 v14, 0xc1000000, v14
	v_rcp_f32_e32 v20, v20
	v_sqrt_f32_e32 v21, v21
	ds_read_b32 v23, v74 offset:8580
	v_add_u32_e32 v15, 0, v13
	v_mul_f32_e32 v14, v57, v14
	ds_write_b32 v15, v22 offset:62720
	v_add_f32_e32 v15, v53, v27
	v_mul_f32_e32 v14, 0x3fb8aa3b, v14
	v_mul_f32_e32 v15, 0xbfb8aa3b, v15
	v_exp_f32_e32 v14, v14
	v_add_f32_e32 v4, 1.0, v4
	v_exp_f32_e32 v15, v15
	v_rcp_f32_e32 v4, v4
	v_mul_f32_e32 v12, v20, v21
	s_waitcnt lgkmcnt(1)
; __device__ __forceinline__ float fexp(float x) { return __expf(x); }
; __device__ __forceinline__ float sigm(float x) { return frcp(1.f + fexp(-x)); }
; __device__ void rg_tile(unsigned char* lds, const Params& p, int l, int b, int ck, int hh, bool outmode) {
;     ...
;     for (int tf = 0; tf < 4; ++tf)
; #pragma unroll
;       for (int jj = 0; jj < 4; ++jj) {
;         const int tt = tf * 16 + lg * 4 + jj;
;         const float r = sigm(ar[tf][jj] + br);
;         const float ig = sigm(ai[tf][jj] + bi);
;         const float la = -8.0f * r * sp;
;         const float a = fexp(la);
;         const float bq = __builtin_amdgcn_sqrtf(fmaxf(1.f - a * a, 0.f)) * ig * XR[tt * 65 + j];
;         AA[(d * 64 + tt) * 64 + j] = a;
;         BQ[(d * 64 + tt) * 64 + j] = bq;
;       }
;   }
;   __syncthreads();
;   {
;     float* SEG = XR;
;     const int seg = tid >> 7, d = (tid >> 6) & 1, j = tid & 63;
;     const int ch = hh * 64 + j;
;     const size_t ci = ((size_t)(b * 36 + ck) * 2 + d) * 256 + ch;
;     float H = 0.f, Ap = 1.f;
; #pragma unroll
;     for (int q = 0; q < 16; ++q) {
;       const int pos = seg * 16 + q;
;       const int tt = d == 0 ? pos : 63 - pos;
;       const float a = AA[(d * 64 + tt) * 64 + j];
;       H = a * H + BQ[(d * 64 + tt) * 64 + j];
	v_mul_f32_e32 v12, v12, v23
	v_add_u32_e32 v13, s0, v13
	v_mfma_f32_16x16x32_bf16 v[0:3], v[16:19], v[0:3], v[8:11]
	v_add_f32_e32 v5, v54, v5
	ds_write_b32 v13, v12
	v_fma_f32 v13, -v14, v14, 1.0
	v_mul_f32_e32 v5, 0xbfb8aa3b, v5
	v_add_f32_e32 v12, 1.0, v15
	v_max_f32_e32 v13, 0, v13
	v_mul_f32_e32 v4, 0xc1000000, v4
	v_exp_f32_e32 v5, v5
	v_rcp_f32_e32 v12, v12
	v_sqrt_f32_e32 v13, v13
	ds_read_b32 v15, v74 offset:8840
	v_mul_f32_e32 v4, v57, v4
	v_add_f32_e32 v0, v53, v0
	v_mul_f32_e32 v4, 0x3fb8aa3b, v4
	v_mul_f32_e32 v0, 0xbfb8aa3b, v0
	v_exp_f32_e32 v4, v4
	v_exp_f32_e32 v0, v0
	v_add_f32_e32 v5, 1.0, v5
	v_mul_f32_e32 v8, v12, v13
	v_or_b32_e32 v9, 0x2300, v84
	v_rcp_f32_e32 v5, v5
	s_waitcnt lgkmcnt(0)
	v_mul_f32_e32 v8, v8, v15
	v_add_u32_e32 v10, 0, v9
	v_add_u32_e32 v9, s0, v9
	ds_write_b32 v9, v8
	v_fma_f32 v8, -v4, v4, 1.0
	ds_write_b32 v10, v14 offset:62720
	v_add_f32_e32 v0, 1.0, v0
	v_max_f32_e32 v8, 0, v8
	v_rcp_f32_e32 v0, v0
	v_sqrt_f32_e32 v8, v8
	ds_read_b32 v9, v74 offset:12220
	v_mul_f32_e32 v5, 0xc1000000, v5
	v_add_f32_e32 v1, v53, v1
	v_mul_f32_e32 v5, v57, v5
	v_mul_f32_e32 v1, 0xbfb8aa3b, v1
	v_mul_f32_e32 v5, 0x3fb8aa3b, v5
	v_exp_f32_e32 v1, v1
	v_exp_f32_e32 v5, v5
	v_mul_f32_e32 v0, v0, v8
	v_or_b32_e32 v8, 0x3000, v84
	s_waitcnt lgkmcnt(0)
	v_mul_f32_e32 v0, v0, v9
	v_add_u32_e32 v9, 0, v8
	ds_write_b32 v9, v4 offset:62720
	v_add_u32_e32 v4, s0, v8
	ds_write_b32 v4, v0
	v_add_f32_e32 v0, 1.0, v1
	v_fma_f32 v1, -v5, v5, 1.0
	v_max_f32_e32 v1, 0, v1
	v_rcp_f32_e32 v0, v0
	v_sqrt_f32_e32 v1, v1
	ds_read_b32 v4, v74 offset:12480
	v_add_f32_e32 v2, v53, v2
	v_mul_f32_e32 v2, 0xbfb8aa3b, v2
	v_mul_f32_e32 v0, v0, v1
	v_exp_f32_e32 v2, v2
	s_waitcnt lgkmcnt(0)
	v_mul_f32_e32 v0, v0, v4
	v_add_f32_e32 v4, v54, v6
	v_mul_f32_e32 v4, 0xbfb8aa3b, v4
	v_exp_f32_e32 v4, v4
	v_or_b32_e32 v1, 0x3100, v84
	v_add_u32_e32 v6, 0, v1
	v_add_u32_e32 v1, s0, v1
	v_add_f32_e32 v4, 1.0, v4
	v_rcp_f32_e32 v4, v4
	ds_write_b32 v1, v0
	ds_write_b32 v6, v5 offset:62720
	v_add_f32_e32 v0, 1.0, v2
	v_mul_f32_e32 v4, 0xc1000000, v4
	v_mul_f32_e32 v4, v57, v4
	v_mul_f32_e32 v4, 0x3fb8aa3b, v4
	v_exp_f32_e32 v4, v4
	v_rcp_f32_e32 v0, v0
	ds_read_b32 v2, v74 offset:12740
	v_add_f32_e32 v3, v53, v3
	v_fma_f32 v1, -v4, v4, 1.0
	v_max_f32_e32 v1, 0, v1
	v_sqrt_f32_e32 v1, v1
	v_mul_f32_e32 v3, 0xbfb8aa3b, v3
	v_exp_f32_e32 v3, v3
	v_lshlrev_b32_e32 v20, 4, v33
	v_mul_f32_e32 v0, v0, v1
	s_waitcnt lgkmcnt(0)
	v_mul_f32_e32 v0, v0, v2
	v_add_f32_e32 v2, v54, v7
	v_mul_f32_e32 v2, 0xbfb8aa3b, v2
	v_exp_f32_e32 v2, v2
	v_or_b32_e32 v1, 0x3200, v84
	v_add_u32_e32 v5, 0, v1
	v_add_u32_e32 v1, s0, v1
	v_add_f32_e32 v2, 1.0, v2
	v_rcp_f32_e32 v2, v2
	ds_write_b32 v1, v0
	ds_write_b32 v5, v4 offset:62720
	v_add_f32_e32 v0, 1.0, v3
	v_mul_f32_e32 v2, 0xc1000000, v2
	v_mul_f32_e32 v2, v57, v2
	v_mul_f32_e32 v2, 0x3fb8aa3b, v2
	v_exp_f32_e32 v2, v2
	v_rcp_f32_e32 v0, v0
	ds_read_b32 v3, v74 offset:13000
	v_lshl_or_b32 v57, v48, 12, v29
	v_fma_f32 v1, -v2, v2, 1.0
	v_max_f32_e32 v1, 0, v1
	v_sqrt_f32_e32 v1, v1
	v_or_b32_e32 v8, 11, v20
	v_sub_u32_e32 v9, 63, v8
	v_cndmask_b32_e32 v8, v9, v8, vcc
	v_mul_f32_e32 v0, v0, v1
	v_or_b32_e32 v1, 0x3300, v84
	s_waitcnt lgkmcnt(0)
	v_mul_f32_e32 v0, v0, v3
	v_add_u32_e32 v3, 0, v1
	ds_write_b32 v3, v2 offset:62720
	v_or_b32_e32 v2, 1, v20
	v_sub_u32_e32 v3, 63, v2
	v_cndmask_b32_e32 v2, v3, v2, vcc
	v_lshlrev_b32_e32 v2, 6, v2
	v_add_lshl_u32 v2, v2, v57, 2
	v_add_u32_e32 v16, 0, v2
	v_add_u32_e32 v22, s0, v2
	v_or_b32_e32 v2, 2, v20
	v_sub_u32_e32 v3, 63, v2
	v_cndmask_b32_e32 v2, v3, v2, vcc
	v_lshlrev_b32_e32 v2, 6, v2
	v_add_u32_e32 v1, s0, v1
	v_add_lshl_u32 v2, v2, v57, 2
	ds_write_b32 v1, v0
	v_sub_u32_e32 v0, 63, v20
	v_add_u32_e32 v23, 0, v2
	v_add_u32_e32 v24, s0, v2
	v_or_b32_e32 v2, 3, v20
	v_cndmask_b32_e32 v0, v0, v20, vcc
	v_sub_u32_e32 v3, 63, v2
	v_lshlrev_b32_e32 v0, 6, v0
	v_cndmask_b32_e32 v2, v3, v2, vcc
	v_add_lshl_u32 v1, v0, v57, 2
	v_lshlrev_b32_e32 v2, 6, v2
	v_add_u32_e32 v0, 0, v1
	v_add_lshl_u32 v2, v2, v57, 2
	s_waitcnt lgkmcnt(0)
	s_barrier
; __device__ void rg_tile(unsigned char* lds, const Params& p, int l, int b, int ck, int hh, bool outmode) {
;     ...
;   {
;     float* SEG = XR;
;     const int seg = tid >> 7, d = (tid >> 6) & 1, j = tid & 63;
;     const int ch = hh * 64 + j;
;     const size_t ci = ((size_t)(b * 36 + ck) * 2 + d) * 256 + ch;
;     float H = 0.f, Ap = 1.f;
; #pragma unroll
;     for (int q = 0; q < 16; ++q) {
;       const int pos = seg * 16 + q;
;       const int tt = d == 0 ? pos : 63 - pos;
;       const float a = AA[(d * 64 + tt) * 64 + j];
;       H = a * H + BQ[(d * 64 + tt) * 64 + j];
;       Ap *= a;
;     }
;     SEG[((seg * 2 + d) * 64 + j) * 2 + 0] = Ap;
;     SEG[((seg * 2 + d) * 64 + j) * 2 + 1] = H;
;     __syncthreads();
;     if (!outmode) {
;       if (seg == 0) {
;         float Ht = 0.f, At = 1.f;
; #pragma unroll
;         for (int sgi = 0; sgi < 4; ++sgi) {
;           const float as = SEG[((sgi * 2 + d) * 64 + j) * 2 + 0], hs = SEG[((sgi * 2 + d) * 64 + j) * 2 + 1];
;           Ht = as * Ht + hs;
;           At *= as;
;         }
;         agg[ci * 2 + 0] = At;
;         agg[ci * 2 + 1] = Ht;
;       }
;     } else {
;       float hc = car_pre;
;       for (int sgi = 0; sgi < seg; ++sgi) {
;         const float as = SEG[((sgi * 2 + d) * 64 + j) * 2 + 0], hs = SEG[((sgi * 2 + d) * 64 + j) * 2 + 1];
;         hc = as * hc + hs;
	v_add_u32_e32 v1, s0, v1
	v_add_u32_e32 v25, 0, v2
	v_add_u32_e32 v26, s0, v2
	ds_read_b32 v2, v0 offset:62720
	ds_read_b32 v3, v1
	ds_read_b32 v4, v16 offset:62720
	ds_read_b32 v5, v22
	ds_read_b32 v58, v23 offset:62720
	ds_read_b32 v6, v24
	ds_read_b32 v12, v25 offset:62720
	ds_read_b32 v7, v26
	s_waitcnt lgkmcnt(6)
	v_fmac_f32_e32 v3, 0, v2
	s_waitcnt lgkmcnt(5)
	v_mul_f32_e32 v14, v2, v4
	v_or_b32_e32 v2, 4, v20
	s_waitcnt lgkmcnt(4)
	v_fmac_f32_e32 v5, v3, v4
	v_sub_u32_e32 v3, 63, v2
	v_cndmask_b32_e32 v2, v3, v2, vcc
	v_lshlrev_b32_e32 v2, 6, v2
	v_add_lshl_u32 v2, v2, v57, 2
	v_add_u32_e32 v27, 0, v2
	v_add_u32_e32 v53, s0, v2
	v_or_b32_e32 v2, 5, v20
	v_sub_u32_e32 v3, 63, v2
	v_cndmask_b32_e32 v2, v3, v2, vcc
	v_lshlrev_b32_e32 v2, 6, v2
	v_add_lshl_u32 v2, v2, v57, 2
	v_add_u32_e32 v54, 0, v2
	v_add_u32_e32 v55, s0, v2
	v_or_b32_e32 v2, 6, v20
	v_sub_u32_e32 v3, 63, v2
	v_cndmask_b32_e32 v2, v3, v2, vcc
	v_lshlrev_b32_e32 v2, 6, v2
	v_add_lshl_u32 v3, v2, v57, 2
	v_add_u32_e32 v2, 0, v3
	v_add_u32_e32 v56, s0, v3
	v_or_b32_e32 v3, 7, v20
	v_sub_u32_e32 v4, 63, v3
	v_cndmask_b32_e32 v3, v4, v3, vcc
	v_lshlrev_b32_e32 v3, 6, v3
	s_waitcnt lgkmcnt(2)
	v_fmac_f32_e32 v6, v5, v58
	v_add_lshl_u32 v3, v3, v57, 2
	v_add_u32_e32 v17, 0, v3
	v_add_u32_e32 v10, s0, v3
	ds_read_b32 v60, v27 offset:62720
	ds_read_b32 v3, v53
	ds_read_b32 v18, v54 offset:62720
	ds_read_b32 v4, v55
	ds_read_b32 v62, v2 offset:62720
	ds_read_b32 v5, v56
	ds_read_b32 v64, v17 offset:62720
	ds_read_b32 v11, v10
	s_waitcnt lgkmcnt(8)
	v_fmac_f32_e32 v7, v6, v12
	s_waitcnt lgkmcnt(6)
	v_fmac_f32_e32 v3, v7, v60
	s_waitcnt lgkmcnt(4)
	v_fmac_f32_e32 v4, v3, v18
	v_or_b32_e32 v3, 8, v20
	s_waitcnt lgkmcnt(2)
	v_fmac_f32_e32 v5, v4, v62
	v_sub_u32_e32 v4, 63, v3
	v_cndmask_b32_e32 v3, v4, v3, vcc
	v_lshlrev_b32_e32 v3, 6, v3
	v_add_lshl_u32 v4, v3, v57, 2
	v_add_u32_e32 v3, 0, v4
	v_add_u32_e32 v21, s0, v4
	v_or_b32_e32 v4, 9, v20
	s_waitcnt lgkmcnt(0)
	v_fmac_f32_e32 v11, v5, v64
	v_sub_u32_e32 v5, 63, v4
	v_cndmask_b32_e32 v4, v5, v4, vcc
	v_lshlrev_b32_e32 v4, 6, v4
	v_add_lshl_u32 v5, v4, v57, 2
	v_add_u32_e32 v4, 0, v5
	v_add_u32_e32 v6, s0, v5
	v_or_b32_e32 v5, 10, v20
	v_sub_u32_e32 v7, 63, v5
	v_cndmask_b32_e32 v5, v7, v5, vcc
	v_lshlrev_b32_e32 v5, 6, v5
	v_lshlrev_b32_e32 v8, 6, v8
	v_add_lshl_u32 v7, v5, v57, 2
	v_add_lshl_u32 v9, v8, v57, 2
	v_add_u32_e32 v5, 0, v7
	v_add_u32_e32 v7, s0, v7
	v_add_u32_e32 v8, 0, v9
	v_add_u32_e32 v9, s0, v9
	ds_read_b32 v66, v3 offset:62720
	ds_read_b32 v15, v21
	ds_read_b32 v59, v4 offset:62720
	ds_read_b32 v13, v6
	ds_read_b32 v61, v5 offset:62720
	ds_read_b32 v19, v7
	ds_read_b32 v63, v8 offset:62720
	ds_read_b32 v65, v9
	s_waitcnt lgkmcnt(6)
	v_fmac_f32_e32 v15, v11, v66
	v_mul_f32_e32 v11, v14, v58
	v_mul_f32_e32 v68, v11, v12
	s_waitcnt lgkmcnt(4)
	v_pk_fma_f32 v[12:13], v[14:15], v[58:59], v[12:13]
	v_or_b32_e32 v11, 12, v20
	v_mov_b32_e32 v69, v13
	s_waitcnt lgkmcnt(3)
	v_pk_mul_f32 v[12:13], v[68:69], v[60:61]
	s_waitcnt lgkmcnt(2)
	v_pk_fma_f32 v[68:69], v[68:69], v[60:61], v[18:19]
	v_pk_mul_f32 v[70:71], v[12:13], v[18:19]
	v_sub_u32_e32 v12, 63, v11
	v_cndmask_b32_e32 v11, v12, v11, vcc
	v_lshlrev_b32_e32 v11, 6, v11
	v_add_lshl_u32 v12, v11, v57, 2
	v_add_u32_e32 v11, 0, v12
	v_add_u32_e32 v15, s0, v12
	v_or_b32_e32 v12, 13, v20
	v_sub_u32_e32 v13, 63, v12
	v_cndmask_b32_e32 v12, v13, v12, vcc
	v_lshlrev_b32_e32 v12, 6, v12
	v_add_lshl_u32 v13, v12, v57, 2
	v_add_u32_e32 v12, 0, v13
	v_add_u32_e32 v18, s0, v13
	v_or_b32_e32 v13, 14, v20
	v_sub_u32_e32 v14, 63, v13
	v_cndmask_b32_e32 v13, v14, v13, vcc
	v_lshlrev_b32_e32 v13, 6, v13
	v_add_lshl_u32 v14, v13, v57, 2
	v_add_u32_e32 v13, 0, v14
	v_add_u32_e32 v19, s0, v14
	v_or_b32_e32 v14, 15, v20
	v_sub_u32_e32 v20, 63, v14
	v_cndmask_b32_e32 v14, v20, v14, vcc
	v_mov_b32_e32 v68, v70
	v_lshlrev_b32_e32 v14, 6, v14
	s_waitcnt lgkmcnt(1)
	v_pk_mul_f32 v[70:71], v[70:71], v[62:63]
	v_add_lshl_u32 v20, v14, v57, 2
	v_lshlrev_b32_e32 v57, 6, v48
	s_waitcnt lgkmcnt(0)
	v_pk_mul_f32 v[70:71], v[70:71], v[64:65]
	v_pk_fma_f32 v[64:65], v[68:69], v[62:63], v[64:65]
	v_or3_b32 v52, v52, v57, v29
	v_mov_b32_e32 v71, v65
	v_add_u32_e32 v14, 0, v20
	v_add_u32_e32 v20, s0, v20
	ds_read_b32 v67, v11 offset:62720
	ds_read_b32 v73, v15
	ds_read_b32 v75, v12 offset:62720
	ds_read_b32 v77, v18
	ds_read_b32 v79, v13 offset:62720
	ds_read_b32 v81, v19
	ds_read_b32 v83, v14 offset:62720
	ds_read_b32 v85, v20
	v_lshl_add_u32 v57, v52, 3, 0
	s_waitcnt lgkmcnt(7)
	v_pk_mul_f32 v[64:65], v[70:71], v[66:67]
	v_mov_b32_e32 v52, v59
	v_mov_b32_e32 v72, v59
	v_pk_mul_f32 v[58:59], v[64:65], v[52:53]
	s_waitcnt lgkmcnt(6)
	v_pk_fma_f32 v[64:65], v[70:71], v[66:67], v[72:73]
	v_mov_b32_e32 v52, v61
	v_mov_b32_e32 v64, v58
	v_mov_b32_e32 v74, v61
	v_pk_mul_f32 v[58:59], v[58:59], v[52:53]
	v_mov_b32_e32 v52, v63
	v_mov_b32_e32 v76, v63
	v_pk_mul_f32 v[58:59], v[58:59], v[52:53]
	s_waitcnt lgkmcnt(4)
	v_pk_fma_f32 v[60:61], v[64:65], v[74:75], v[76:77]
	v_mov_b32_e32 v78, v67
	v_mov_b32_e32 v59, v61
	s_waitcnt lgkmcnt(3)
	v_pk_mul_f32 v[60:61], v[58:59], v[78:79]
	v_mov_b32_e32 v52, v75
	v_mov_b32_e32 v80, v75
	v_pk_mul_f32 v[60:61], v[60:61], v[52:53]
	s_waitcnt lgkmcnt(2)
	v_pk_fma_f32 v[58:59], v[58:59], v[78:79], v[80:81]
	v_mov_b32_e32 v52, v79
	v_mov_b32_e32 v58, v60
	v_mov_b32_e32 v82, v79
	v_pk_mul_f32 v[60:61], v[60:61], v[52:53]
	s_waitcnt lgkmcnt(1)
	v_mov_b32_e32 v52, v83
	v_mov_b32_e32 v84, v83
	v_pk_mul_f32 v[60:61], v[60:61], v[52:53]
	s_waitcnt lgkmcnt(0)
	v_pk_fma_f32 v[58:59], v[58:59], v[82:83], v[84:85]
	v_cmp_lt_i32_e32 vcc, 0, v33
	v_mov_b32_e32 v61, v59
	ds_write_b64 v57, v[60:61]
	s_waitcnt lgkmcnt(0)
	s_barrier
	s_and_saveexec_b64 s[0:1], vcc
	s_cbranch_execz .LBB0_713
	v_lshlrev_b32_e32 v29, 3, v29
	v_lshl_or_b32 v29, v48, 9, v29
	v_add_u32_e32 v29, 0, v29
	s_mov_b64 s[2:3], 0
